# rstd table fill: SSQ row loads of all units issued first, single wait, then reduce (4 GEMM phases)
# speedup vs baseline: 1.0007x; 1.0007x over previous
; #define PG8_LAS __attribute__((address_space(3)))
;     __host__ __device__ bool next(int i, Unit& u) const {
;         const long L = (long)i * G + c; if (L >= nwg) return false;
;         int wgid = (int)L; { const int q = nwg / NXCD, r = nwg % NXCD, xcd = wgid % NXCD, off = wgid / NXCD; wgid = (xcd < r ? xcd * (q + 1) : r * (q + 1) + (xcd - r) * q) + off; }
;         const int nig = WGM * nN, gid = wgid / nig, fm = gid * WGM, gsz = (nM - fm) < WGM ? (nM - fm) : WGM;
;         u.pm = fm + ((wgid % nig) % gsz); u.pn = (wgid % nig) / gsz; return true;
; template <class Sched> __device__ __forceinline__ void fill_rstd_table(PG8_LAS float* tab, const float* ssq, const Sched& S) {
;     const int tid = threadIdx.x, r = tid >> 1, hf = tid & 1; Unit u;
;     for (int i = 0; S.next(i, u); ++i) { const f32x4* p = (const f32x4*)(ssq + (size_t)(u.pm * BM + r) * 32 + hf * 16); float s = 0.f;
; #pragma unroll
;         for (int j = 0; j < 4; ++j) { const f32x4 a = p[j]; s += (a[0] + a[1]) + (a[2] + a[3]); }
.LBB0_274:
	s_or_b64 exec, exec, s[0:1]
	s_ashr_i32 s0, s84, 31
	v_writelane_b32 v237, s0, 46
	s_mov_b32 s0, s84
	v_writelane_b32 v237, s0, 47
	v_and_b32_e32 v2, 1, v172
	v_readlane_b32 s0, v237, 48
	v_lshrrev_b32_e32 v173, 1, v172
	s_waitcnt lgkmcnt(0)
	v_lshlrev_b32_e32 v0, 6, v2
	v_mov_b32_e32 v1, 0
	v_readlane_b32 s1, v237, 49
	v_mbcnt_hi_u32_b32 v175, -1, v44
	s_ashr_i32 s67, s66, 31
	v_lshl_add_u64 v[128:129], s[0:1], 0, v[0:1]
	v_lshl_add_u32 v0, v173, 2, 0
	v_cmp_eq_u32_e64 s[0:1], 0, v2
	v_add_u32_e32 v174, 0x20000, v0
	v_and_b32_e32 v178, 64, v175
	v_writelane_b32 v237, s0, 50
	v_mov_b64_e32 v[0:1], 0x2ff
	s_movk_i32 s6, 0x61
	v_mov_b32_e32 v2, 0x358637bd
	s_mov_b32 s7, 0xf800000
	v_mov_b32_e32 v3, 0x260
	v_xor_b32_e32 v176, 1, v175
	v_add_u32_e32 v177, 64, v178
	s_mov_b64 s[2:3], s[66:67]
	v_mov_b32_e32 v4, v174
	s_barrier
	v_writelane_b32 v237, s1, 51
	s_waitcnt vmcnt(0)
	s_mov_b32 s14, 0
	v_cmp_gt_i64_e32 vcc, s[2:3], v[0:1]
	s_cbranch_vccnz .Lfill0_p2
	s_ashr_i32 s0, s2, 31
	s_lshr_b32 s0, s0, 29
	s_add_i32 s0, s2, s0
	s_ashr_i32 s1, s0, 3
	s_and_b32 s0, s0, -8
	s_sub_i32 s0, s2, s0
	s_cmp_lt_i32 s0, 0
	s_cselect_b32 s4, s6, 0x60
	s_mul_i32 s0, s0, s4
	s_add_i32 s0, s0, s1
	s_mul_hi_i32 s1, s0, 0x2aaaaaab
	s_lshr_b32 s4, s1, 31
	s_ashr_i32 s1, s1, 5
	s_add_i32 s1, s1, s4
	s_lshl_b32 s4, s1, 3
	s_sub_i32 s5, 32, s4
	s_min_i32 s5, s5, 8
	s_abs_i32 s5, s5
	v_cvt_f32_u32_e32 v5, s5
	s_sub_i32 s12, 0, s5
	s_mulk_i32 s1, 0xc0
	s_sub_i32 s0, s0, s1
	v_rcp_iflag_f32_e32 v5, v5
	s_ashr_i32 s1, s0, 31
	s_abs_i32 s0, s0
	v_cmp_lt_i32_e32 vcc, v176, v177
	v_mul_f32_e32 v5, 0x4f7ffffe, v5
	v_cvt_u32_f32_e32 v5, v5
	v_cndmask_b32_e32 v22, v175, v176, vcc
	v_readfirstlane_b32 s13, v5
	s_mul_i32 s12, s12, s13
	s_mul_hi_u32 s12, s13, s12
	s_add_i32 s13, s13, s12
	s_mul_hi_u32 s12, s0, s13
	s_mul_i32 s12, s12, s5
	s_sub_i32 s0, s0, s12
	s_sub_i32 s12, s0, s5
	s_cmp_ge_u32 s0, s5
	s_cselect_b32 s0, s12, s0
	s_sub_i32 s12, s0, s5
	s_cmp_ge_u32 s0, s5
	s_cselect_b32 s0, s12, s0
	s_xor_b32 s0, s0, s1
	s_sub_i32 s0, s0, s1
	s_add_i32 s4, s4, s0
	s_waitcnt lgkmcnt(0)
	v_lshl_add_u32 v6, s4, 8, v173
	v_ashrrev_i32_e32 v7, 31, v6
	v_lshlrev_b64 v[6:7], 7, v[6:7]
	v_lshl_add_u64 v[18:19], v[128:129], 0, v[6:7]
	global_load_dwordx4 v[24:27], v[18:19], off
	global_load_dwordx4 v[28:31], v[18:19], off offset:16
	global_load_dwordx4 v[32:35], v[18:19], off offset:32
	s_nop 0
	global_load_dwordx4 v[36:39], v[18:19], off offset:48
	v_readlane_b32 s0, v237, 47
	s_add_u32 s2, s2, s0
	v_readlane_b32 s0, v237, 46
	s_addc_u32 s3, s3, s0
	s_add_u32 s14, s14, 1
	v_cmp_gt_i64_e32 vcc, s[2:3], v[0:1]
	s_cbranch_vccnz .Lfill0_p2
	s_ashr_i32 s0, s2, 31
	s_lshr_b32 s0, s0, 29
	s_add_i32 s0, s2, s0
	s_ashr_i32 s1, s0, 3
	s_and_b32 s0, s0, -8
	s_sub_i32 s0, s2, s0
	s_cmp_lt_i32 s0, 0
	s_cselect_b32 s4, s6, 0x60
	s_mul_i32 s0, s0, s4
	s_add_i32 s0, s0, s1
	s_mul_hi_i32 s1, s0, 0x2aaaaaab
	s_lshr_b32 s4, s1, 31
	s_ashr_i32 s1, s1, 5
	s_add_i32 s1, s1, s4
	s_lshl_b32 s4, s1, 3
	s_sub_i32 s5, 32, s4
	s_min_i32 s5, s5, 8
	s_abs_i32 s5, s5
	v_cvt_f32_u32_e32 v5, s5
	s_sub_i32 s12, 0, s5
	s_mulk_i32 s1, 0xc0
	s_sub_i32 s0, s0, s1
	v_rcp_iflag_f32_e32 v5, v5
	s_ashr_i32 s1, s0, 31
	s_abs_i32 s0, s0
	v_cmp_lt_i32_e32 vcc, v176, v177
	v_mul_f32_e32 v5, 0x4f7ffffe, v5
	v_cvt_u32_f32_e32 v5, v5
	v_cndmask_b32_e32 v22, v175, v176, vcc
	v_readfirstlane_b32 s13, v5
	s_mul_i32 s12, s12, s13
	s_mul_hi_u32 s12, s13, s12
	s_add_i32 s13, s13, s12
	s_mul_hi_u32 s12, s0, s13
	s_mul_i32 s12, s12, s5
	s_sub_i32 s0, s0, s12
	s_sub_i32 s12, s0, s5
	s_cmp_ge_u32 s0, s5
	s_cselect_b32 s0, s12, s0
	s_sub_i32 s12, s0, s5
	s_cmp_ge_u32 s0, s5
	s_cselect_b32 s0, s12, s0
	s_xor_b32 s0, s0, s1
	s_sub_i32 s0, s0, s1
	s_add_i32 s4, s4, s0
	s_waitcnt lgkmcnt(0)
	v_lshl_add_u32 v6, s4, 8, v173
	v_ashrrev_i32_e32 v7, 31, v6
	v_lshlrev_b64 v[6:7], 7, v[6:7]
	v_lshl_add_u64 v[18:19], v[128:129], 0, v[6:7]
	global_load_dwordx4 v[40:43], v[18:19], off
	global_load_dwordx4 v[44:47], v[18:19], off offset:16
	global_load_dwordx4 v[48:51], v[18:19], off offset:32
	s_nop 0
	global_load_dwordx4 v[52:55], v[18:19], off offset:48
	v_readlane_b32 s0, v237, 47
	s_add_u32 s2, s2, s0
	v_readlane_b32 s0, v237, 46
	s_addc_u32 s3, s3, s0
	s_add_u32 s14, s14, 1
	v_cmp_gt_i64_e32 vcc, s[2:3], v[0:1]
	s_cbranch_vccnz .Lfill0_p2
	s_ashr_i32 s0, s2, 31
	s_lshr_b32 s0, s0, 29
	s_add_i32 s0, s2, s0
	s_ashr_i32 s1, s0, 3
	s_and_b32 s0, s0, -8
	s_sub_i32 s0, s2, s0
	s_cmp_lt_i32 s0, 0
	s_cselect_b32 s4, s6, 0x60
	s_mul_i32 s0, s0, s4
	s_add_i32 s0, s0, s1
	s_mul_hi_i32 s1, s0, 0x2aaaaaab
	s_lshr_b32 s4, s1, 31
	s_ashr_i32 s1, s1, 5
	s_add_i32 s1, s1, s4
	s_lshl_b32 s4, s1, 3
	s_sub_i32 s5, 32, s4
	s_min_i32 s5, s5, 8
	s_abs_i32 s5, s5
	v_cvt_f32_u32_e32 v5, s5
	s_sub_i32 s12, 0, s5
	s_mulk_i32 s1, 0xc0
	s_sub_i32 s0, s0, s1
	v_rcp_iflag_f32_e32 v5, v5
	s_ashr_i32 s1, s0, 31
	s_abs_i32 s0, s0
	v_cmp_lt_i32_e32 vcc, v176, v177
	v_mul_f32_e32 v5, 0x4f7ffffe, v5
	v_cvt_u32_f32_e32 v5, v5
	v_cndmask_b32_e32 v22, v175, v176, vcc
	v_readfirstlane_b32 s13, v5
	s_mul_i32 s12, s12, s13
	s_mul_hi_u32 s12, s13, s12
	s_add_i32 s13, s13, s12
	s_mul_hi_u32 s12, s0, s13
	s_mul_i32 s12, s12, s5
	s_sub_i32 s0, s0, s12
	s_sub_i32 s12, s0, s5
	s_cmp_ge_u32 s0, s5
	s_cselect_b32 s0, s12, s0
	s_sub_i32 s12, s0, s5
	s_cmp_ge_u32 s0, s5
	s_cselect_b32 s0, s12, s0
	s_xor_b32 s0, s0, s1
	s_sub_i32 s0, s0, s1
	s_add_i32 s4, s4, s0
	s_waitcnt lgkmcnt(0)
	v_lshl_add_u32 v6, s4, 8, v173
	v_ashrrev_i32_e32 v7, 31, v6
	v_lshlrev_b64 v[6:7], 7, v[6:7]
	v_lshl_add_u64 v[18:19], v[128:129], 0, v[6:7]
	global_load_dwordx4 v[56:59], v[18:19], off
	global_load_dwordx4 v[60:63], v[18:19], off offset:16
	global_load_dwordx4 v[64:67], v[18:19], off offset:32
	s_nop 0
	global_load_dwordx4 v[68:71], v[18:19], off offset:48
	v_readlane_b32 s0, v237, 47
	s_add_u32 s2, s2, s0
	v_readlane_b32 s0, v237, 46
	s_addc_u32 s3, s3, s0
	s_add_u32 s14, s14, 1
; template <class Sched> __device__ __forceinline__ void fill_rstd_table(PG8_LAS float* tab, const float* ssq, const Sched& S) {
;     ...
;     for (int i = 0; S.next(i, u); ++i) { const f32x4* p = (const f32x4*)(ssq + (size_t)(u.pm * BM + r) * 32 + hf * 16); float s = 0.f;
; #pragma unroll
;         for (int j = 0; j < 4; ++j) { const f32x4 a = p[j]; s += (a[0] + a[1]) + (a[2] + a[3]); }
;         s += __shfl_xor(s, 1);
;         if (hf == 0) tab[i * 256 + r] = 1.0f / sqrtf(s * (1.0f / 2048.0f) + RMS_EPS); }
.Lfill0_p2:
	s_waitcnt vmcnt(0)
	s_cmp_le_u32 s14, 0
	s_cbranch_scc1 .Lfill0_done
	v_mov_b32_e32 v6, v24
	v_mov_b32_e32 v7, v25
	v_mov_b32_e32 v8, v26
	v_mov_b32_e32 v9, v27
	v_mov_b32_e32 v10, v28
	v_mov_b32_e32 v11, v29
	v_mov_b32_e32 v12, v30
	v_mov_b32_e32 v13, v31
	v_mov_b32_e32 v14, v32
	v_mov_b32_e32 v15, v33
	v_mov_b32_e32 v16, v34
	v_mov_b32_e32 v17, v35
	v_mov_b32_e32 v18, v36
	v_mov_b32_e32 v19, v37
	v_mov_b32_e32 v20, v38
	v_mov_b32_e32 v21, v39
	v_add_f32_e32 v5, v6, v7
	v_add_f32_e32 v6, v8, v9
	v_add_f32_e32 v7, v10, v11
	v_add_f32_e32 v8, v12, v13
	v_add_f32_e32 v5, v5, v6
	v_add_f32_e32 v9, v14, v15
	v_add_f32_e32 v10, v16, v17
	v_add_f32_e32 v6, v7, v8
	v_add_f32_e32 v5, 0, v5
	v_add_f32_e32 v11, v18, v19
	v_add_f32_e32 v12, v20, v21
	v_add_f32_e32 v7, v9, v10
	v_add_f32_e32 v5, v5, v6
	v_add_f32_e32 v8, v11, v12
	v_add_f32_e32 v5, v5, v7
	v_add_f32_e32 v5, v5, v8
	v_lshlrev_b32_e32 v6, 2, v22
	ds_bpermute_b32 v6, v6, v5
	s_mov_b64 s[4:5], exec
	v_readlane_b32 s0, v237, 50
	v_readlane_b32 s1, v237, 51
	s_and_b64 s[0:1], s[4:5], s[0:1]
	s_mov_b64 exec, s[0:1]
	s_cbranch_execz .Lfill0_j0
	s_waitcnt lgkmcnt(0)
	v_add_f32_e32 v5, v5, v6
	v_fmamk_f32 v5, v5, 0x3a000000, v2
	v_mul_f32_e32 v6, 0x4f800000, v5
	v_cmp_gt_f32_e32 vcc, s7, v5
	s_nop 1
	v_cndmask_b32_e32 v5, v5, v6, vcc
	v_sqrt_f32_e32 v6, v5
	s_nop 0
	v_add_u32_e32 v7, -1, v6
	v_fma_f32 v9, -v7, v6, v5
	v_add_u32_e32 v8, 1, v6
	v_cmp_ge_f32_e64 s[0:1], 0, v9
	s_nop 1
	v_cndmask_b32_e64 v7, v6, v7, s[0:1]
	v_fma_f32 v6, -v8, v6, v5
	v_cmp_lt_f32_e64 s[0:1], 0, v6
	s_nop 1
	v_cndmask_b32_e64 v6, v7, v8, s[0:1]
	v_mul_f32_e32 v7, 0x37800000, v6
	v_cndmask_b32_e32 v6, v6, v7, vcc
	v_cmp_class_f32_e32 vcc, v5, v3
	s_nop 1
	v_cndmask_b32_e32 v5, v6, v5, vcc
	v_div_scale_f32 v6, s[0:1], v5, v5, 1.0
	v_rcp_f32_e32 v7, v6
	s_nop 0
	v_fma_f32 v8, -v6, v7, 1.0
	v_fmac_f32_e32 v7, v8, v7
	v_div_scale_f32 v8, vcc, 1.0, v5, 1.0
	v_mul_f32_e32 v9, v8, v7
	v_fma_f32 v10, -v6, v9, v8
	v_fmac_f32_e32 v9, v10, v7
	v_fma_f32 v6, -v6, v9, v8
	v_div_fmas_f32 v6, v6, v7, v9
	v_div_fixup_f32 v5, v6, v5, 1.0
	ds_write_b32 v4, v5
.Lfill0_j0:
	s_or_b64 exec, exec, s[4:5]
	v_add_u32_e32 v4, 0x400, v4
	s_cmp_le_u32 s14, 1
	s_cbranch_scc1 .Lfill0_done
	v_mov_b32_e32 v6, v40
	v_mov_b32_e32 v7, v41
	v_mov_b32_e32 v8, v42
	v_mov_b32_e32 v9, v43
	v_mov_b32_e32 v10, v44
	v_mov_b32_e32 v11, v45
	v_mov_b32_e32 v12, v46
	v_mov_b32_e32 v13, v47
	v_mov_b32_e32 v14, v48
	v_mov_b32_e32 v15, v49
	v_mov_b32_e32 v16, v50
	v_mov_b32_e32 v17, v51
	v_mov_b32_e32 v18, v52
	v_mov_b32_e32 v19, v53
	v_mov_b32_e32 v20, v54
	v_mov_b32_e32 v21, v55
	v_add_f32_e32 v5, v6, v7
	v_add_f32_e32 v6, v8, v9
	v_add_f32_e32 v7, v10, v11
	v_add_f32_e32 v8, v12, v13
	v_add_f32_e32 v5, v5, v6
	v_add_f32_e32 v9, v14, v15
	v_add_f32_e32 v10, v16, v17
	v_add_f32_e32 v6, v7, v8
	v_add_f32_e32 v5, 0, v5
	v_add_f32_e32 v11, v18, v19
	v_add_f32_e32 v12, v20, v21
	v_add_f32_e32 v7, v9, v10
	v_add_f32_e32 v5, v5, v6
	v_add_f32_e32 v8, v11, v12
	v_add_f32_e32 v5, v5, v7
	v_add_f32_e32 v5, v5, v8
	v_lshlrev_b32_e32 v6, 2, v22
	ds_bpermute_b32 v6, v6, v5
	s_mov_b64 s[4:5], exec
	v_readlane_b32 s0, v237, 50
	v_readlane_b32 s1, v237, 51
	s_and_b64 s[0:1], s[4:5], s[0:1]
	s_mov_b64 exec, s[0:1]
	s_cbranch_execz .Lfill0_j1
	s_waitcnt lgkmcnt(0)
	v_add_f32_e32 v5, v5, v6
	v_fmamk_f32 v5, v5, 0x3a000000, v2
	v_mul_f32_e32 v6, 0x4f800000, v5
	v_cmp_gt_f32_e32 vcc, s7, v5
	s_nop 1
	v_cndmask_b32_e32 v5, v5, v6, vcc
	v_sqrt_f32_e32 v6, v5
	s_nop 0
	v_add_u32_e32 v7, -1, v6
	v_fma_f32 v9, -v7, v6, v5
	v_add_u32_e32 v8, 1, v6
	v_cmp_ge_f32_e64 s[0:1], 0, v9
	s_nop 1
	v_cndmask_b32_e64 v7, v6, v7, s[0:1]
	v_fma_f32 v6, -v8, v6, v5
	v_cmp_lt_f32_e64 s[0:1], 0, v6
	s_nop 1
	v_cndmask_b32_e64 v6, v7, v8, s[0:1]
	v_mul_f32_e32 v7, 0x37800000, v6
	v_cndmask_b32_e32 v6, v6, v7, vcc
	v_cmp_class_f32_e32 vcc, v5, v3
	s_nop 1
	v_cndmask_b32_e32 v5, v6, v5, vcc
	v_div_scale_f32 v6, s[0:1], v5, v5, 1.0
	v_rcp_f32_e32 v7, v6
	s_nop 0
	v_fma_f32 v8, -v6, v7, 1.0
	v_fmac_f32_e32 v7, v8, v7
	v_div_scale_f32 v8, vcc, 1.0, v5, 1.0
	v_mul_f32_e32 v9, v8, v7
	v_fma_f32 v10, -v6, v9, v8
	v_fmac_f32_e32 v9, v10, v7
	v_fma_f32 v6, -v6, v9, v8
	v_div_fmas_f32 v6, v6, v7, v9
	v_div_fixup_f32 v5, v6, v5, 1.0
	ds_write_b32 v4, v5
.Lfill0_j1:
	s_or_b64 exec, exec, s[4:5]
	v_add_u32_e32 v4, 0x400, v4
	s_cmp_le_u32 s14, 2
	s_cbranch_scc1 .Lfill0_done
	v_mov_b32_e32 v6, v56
	v_mov_b32_e32 v7, v57
	v_mov_b32_e32 v8, v58
	v_mov_b32_e32 v9, v59
	v_mov_b32_e32 v10, v60
	v_mov_b32_e32 v11, v61
	v_mov_b32_e32 v12, v62
	v_mov_b32_e32 v13, v63
	v_mov_b32_e32 v14, v64
	v_mov_b32_e32 v15, v65
	v_mov_b32_e32 v16, v66
	v_mov_b32_e32 v17, v67
	v_mov_b32_e32 v18, v68
	v_mov_b32_e32 v19, v69
	v_mov_b32_e32 v20, v70
	v_mov_b32_e32 v21, v71
	v_add_f32_e32 v5, v6, v7
	v_add_f32_e32 v6, v8, v9
	v_add_f32_e32 v7, v10, v11
	v_add_f32_e32 v8, v12, v13
	v_add_f32_e32 v5, v5, v6
	v_add_f32_e32 v9, v14, v15
	v_add_f32_e32 v10, v16, v17
	v_add_f32_e32 v6, v7, v8
	v_add_f32_e32 v5, 0, v5
	v_add_f32_e32 v11, v18, v19
	v_add_f32_e32 v12, v20, v21
	v_add_f32_e32 v7, v9, v10
	v_add_f32_e32 v5, v5, v6
	v_add_f32_e32 v8, v11, v12
	v_add_f32_e32 v5, v5, v7
	v_add_f32_e32 v5, v5, v8
	v_lshlrev_b32_e32 v6, 2, v22
	ds_bpermute_b32 v6, v6, v5
	s_mov_b64 s[4:5], exec
	v_readlane_b32 s0, v237, 50
	v_readlane_b32 s1, v237, 51
	s_and_b64 s[0:1], s[4:5], s[0:1]
	s_mov_b64 exec, s[0:1]
	s_cbranch_execz .Lfill0_j2
	s_waitcnt lgkmcnt(0)
	v_add_f32_e32 v5, v5, v6
	v_fmamk_f32 v5, v5, 0x3a000000, v2
	v_mul_f32_e32 v6, 0x4f800000, v5
	v_cmp_gt_f32_e32 vcc, s7, v5
	s_nop 1
	v_cndmask_b32_e32 v5, v5, v6, vcc
	v_sqrt_f32_e32 v6, v5
	s_nop 0
	v_add_u32_e32 v7, -1, v6
	v_fma_f32 v9, -v7, v6, v5
	v_add_u32_e32 v8, 1, v6
	v_cmp_ge_f32_e64 s[0:1], 0, v9
	s_nop 1
	v_cndmask_b32_e64 v7, v6, v7, s[0:1]
	v_fma_f32 v6, -v8, v6, v5
	v_cmp_lt_f32_e64 s[0:1], 0, v6
	s_nop 1
	v_cndmask_b32_e64 v6, v7, v8, s[0:1]
	v_mul_f32_e32 v7, 0x37800000, v6
	v_cndmask_b32_e32 v6, v6, v7, vcc
	v_cmp_class_f32_e32 vcc, v5, v3
	s_nop 1
	v_cndmask_b32_e32 v5, v6, v5, vcc
	v_div_scale_f32 v6, s[0:1], v5, v5, 1.0
	v_rcp_f32_e32 v7, v6
	s_nop 0
	v_fma_f32 v8, -v6, v7, 1.0
	v_fmac_f32_e32 v7, v8, v7
	v_div_scale_f32 v8, vcc, 1.0, v5, 1.0
	v_mul_f32_e32 v9, v8, v7
	v_fma_f32 v10, -v6, v9, v8
	v_fmac_f32_e32 v9, v10, v7
	v_fma_f32 v6, -v6, v9, v8
	v_div_fmas_f32 v6, v6, v7, v9
	v_div_fixup_f32 v5, v6, v5, 1.0
	ds_write_b32 v4, v5
.Lfill0_j2:
	s_or_b64 exec, exec, s[4:5]
	v_add_u32_e32 v4, 0x400, v4
.Lfill0_done:
	s_branch .LBB0_277

; #define PG8_LAS __attribute__((address_space(3)))
;     __host__ __device__ bool next(int i, Unit& u) const {
;         const long L = (long)i * G + c; if (L >= nwg) return false;
;         int wgid = (int)L; { const int q = nwg / NXCD, r = nwg % NXCD, xcd = wgid % NXCD, off = wgid / NXCD; wgid = (xcd < r ? xcd * (q + 1) : r * (q + 1) + (xcd - r) * q) + off; }
;         const int nig = WGM * nN, gid = wgid / nig, fm = gid * WGM, gsz = (nM - fm) < WGM ? (nM - fm) : WGM;
;         u.pm = fm + ((wgid % nig) % gsz); u.pn = (wgid % nig) / gsz; return true;
; template <class Sched> __device__ __forceinline__ void fill_rstd_table(PG8_LAS float* tab, const float* ssq, const Sched& S) {
;     const int tid = threadIdx.x, r = tid >> 1, hf = tid & 1; Unit u;
;     for (int i = 0; S.next(i, u); ++i) { const f32x4* p = (const f32x4*)(ssq + (size_t)(u.pm * BM + r) * 32 + hf * 16); float s = 0.f;
; #pragma unroll
;         for (int j = 0; j < 4; ++j) { const f32x4 a = p[j]; s += (a[0] + a[1]) + (a[2] + a[3]); }
.LBB0_821:
	s_andn2_b64 vcc, exec, s[0:1]
	s_ashr_i32 s0, s33, 3
	v_writelane_b32 v236, s0, 11
	s_cbranch_vccnz .LBB0_1005
	v_mov_b64_e32 v[0:1], 0x57f
	s_movk_i32 s6, 0xb1
	v_mov_b32_e32 v2, 0x358637bd
	s_mov_b32 s7, 0xf800000
	v_mov_b32_e32 v3, 0x260
	s_mov_b64 s[2:3], s[66:67]
	s_waitcnt vmcnt(11)
	v_mov_b32_e32 v4, v174
	s_waitcnt vmcnt(0)
	s_mov_b32 s11, 0
	v_cmp_gt_i64_e32 vcc, s[2:3], v[0:1]
	s_cbranch_vccnz .Lfill1_p2
	s_ashr_i32 s0, s2, 31
	s_lshr_b32 s0, s0, 29
	s_add_i32 s0, s2, s0
	s_ashr_i32 s1, s0, 3
	s_and_b32 s0, s0, -8
	s_sub_i32 s0, s2, s0
	s_cmp_lt_i32 s0, 0
	s_cselect_b32 s4, s6, 0xb0
	s_mul_i32 s0, s0, s4
	s_add_i32 s0, s0, s1
	s_mul_hi_i32 s1, s0, 0x2e8ba2e9
	s_lshr_b32 s4, s1, 31
	s_ashr_i32 s1, s1, 6
	s_add_i32 s1, s1, s4
	s_lshl_b32 s4, s1, 3
	s_sub_i32 s5, 32, s4
	s_min_i32 s5, s5, 8
	s_abs_i32 s5, s5
	v_cvt_f32_u32_e32 v5, s5
	s_sub_i32 s8, 0, s5
	s_mulk_i32 s1, 0x160
	s_sub_i32 s0, s0, s1
	v_rcp_iflag_f32_e32 v5, v5
	s_ashr_i32 s1, s0, 31
	s_abs_i32 s0, s0
	v_cmp_lt_i32_e32 vcc, v176, v177
	v_mul_f32_e32 v5, 0x4f7ffffe, v5
	v_cvt_u32_f32_e32 v5, v5
	v_cndmask_b32_e32 v22, v175, v176, vcc
	v_readfirstlane_b32 s9, v5
	s_mul_i32 s8, s8, s9
	s_mul_hi_u32 s8, s9, s8
	s_add_i32 s9, s9, s8
	s_mul_hi_u32 s8, s0, s9
	s_mul_i32 s8, s8, s5
	s_sub_i32 s0, s0, s8
	s_sub_i32 s8, s0, s5
	s_cmp_ge_u32 s0, s5
	s_cselect_b32 s0, s8, s0
	s_sub_i32 s8, s0, s5
	s_cmp_ge_u32 s0, s5
	s_cselect_b32 s0, s8, s0
	s_xor_b32 s0, s0, s1
	s_sub_i32 s0, s0, s1
	s_add_i32 s4, s4, s0
	s_waitcnt lgkmcnt(0)
	v_lshl_add_u32 v6, s4, 8, v173
	v_ashrrev_i32_e32 v7, 31, v6
	v_lshlrev_b64 v[6:7], 7, v[6:7]
	v_lshl_add_u64 v[18:19], v[128:129], 0, v[6:7]
	global_load_dwordx4 v[24:27], v[18:19], off
	global_load_dwordx4 v[28:31], v[18:19], off offset:16
	global_load_dwordx4 v[32:35], v[18:19], off offset:32
	s_nop 0
	global_load_dwordx4 v[36:39], v[18:19], off offset:48
	v_readlane_b32 s0, v236, 0
	s_add_u32 s2, s2, s0
	v_readlane_b32 s0, v236, 1
	s_addc_u32 s3, s3, s0
	s_add_u32 s11, s11, 1
	v_cmp_gt_i64_e32 vcc, s[2:3], v[0:1]
	s_cbranch_vccnz .Lfill1_p2
	s_ashr_i32 s0, s2, 31
	s_lshr_b32 s0, s0, 29
	s_add_i32 s0, s2, s0
	s_ashr_i32 s1, s0, 3
	s_and_b32 s0, s0, -8
	s_sub_i32 s0, s2, s0
	s_cmp_lt_i32 s0, 0
	s_cselect_b32 s4, s6, 0xb0
	s_mul_i32 s0, s0, s4
	s_add_i32 s0, s0, s1
	s_mul_hi_i32 s1, s0, 0x2e8ba2e9
	s_lshr_b32 s4, s1, 31
	s_ashr_i32 s1, s1, 6
	s_add_i32 s1, s1, s4
	s_lshl_b32 s4, s1, 3
	s_sub_i32 s5, 32, s4
	s_min_i32 s5, s5, 8
	s_abs_i32 s5, s5
	v_cvt_f32_u32_e32 v5, s5
	s_sub_i32 s8, 0, s5
	s_mulk_i32 s1, 0x160
	s_sub_i32 s0, s0, s1
	v_rcp_iflag_f32_e32 v5, v5
	s_ashr_i32 s1, s0, 31
	s_abs_i32 s0, s0
	v_cmp_lt_i32_e32 vcc, v176, v177
	v_mul_f32_e32 v5, 0x4f7ffffe, v5
	v_cvt_u32_f32_e32 v5, v5
	v_cndmask_b32_e32 v22, v175, v176, vcc
	v_readfirstlane_b32 s9, v5
	s_mul_i32 s8, s8, s9
	s_mul_hi_u32 s8, s9, s8
	s_add_i32 s9, s9, s8
	s_mul_hi_u32 s8, s0, s9
	s_mul_i32 s8, s8, s5
	s_sub_i32 s0, s0, s8
	s_sub_i32 s8, s0, s5
	s_cmp_ge_u32 s0, s5
	s_cselect_b32 s0, s8, s0
	s_sub_i32 s8, s0, s5
	s_cmp_ge_u32 s0, s5
	s_cselect_b32 s0, s8, s0
	s_xor_b32 s0, s0, s1
	s_sub_i32 s0, s0, s1
	s_add_i32 s4, s4, s0
	s_waitcnt lgkmcnt(0)
	v_lshl_add_u32 v6, s4, 8, v173
	v_ashrrev_i32_e32 v7, 31, v6
	v_lshlrev_b64 v[6:7], 7, v[6:7]
	v_lshl_add_u64 v[18:19], v[128:129], 0, v[6:7]
	global_load_dwordx4 v[40:43], v[18:19], off
	global_load_dwordx4 v[44:47], v[18:19], off offset:16
	global_load_dwordx4 v[48:51], v[18:19], off offset:32
	s_nop 0
	global_load_dwordx4 v[52:55], v[18:19], off offset:48
	v_readlane_b32 s0, v236, 0
	s_add_u32 s2, s2, s0
	v_readlane_b32 s0, v236, 1
	s_addc_u32 s3, s3, s0
	s_add_u32 s11, s11, 1
	v_cmp_gt_i64_e32 vcc, s[2:3], v[0:1]
	s_cbranch_vccnz .Lfill1_p2
	s_ashr_i32 s0, s2, 31
	s_lshr_b32 s0, s0, 29
	s_add_i32 s0, s2, s0
	s_ashr_i32 s1, s0, 3
	s_and_b32 s0, s0, -8
	s_sub_i32 s0, s2, s0
	s_cmp_lt_i32 s0, 0
	s_cselect_b32 s4, s6, 0xb0
	s_mul_i32 s0, s0, s4
	s_add_i32 s0, s0, s1
	s_mul_hi_i32 s1, s0, 0x2e8ba2e9
	s_lshr_b32 s4, s1, 31
	s_ashr_i32 s1, s1, 6
	s_add_i32 s1, s1, s4
	s_lshl_b32 s4, s1, 3
	s_sub_i32 s5, 32, s4
	s_min_i32 s5, s5, 8
	s_abs_i32 s5, s5
	v_cvt_f32_u32_e32 v5, s5
	s_sub_i32 s8, 0, s5
	s_mulk_i32 s1, 0x160
	s_sub_i32 s0, s0, s1
	v_rcp_iflag_f32_e32 v5, v5
	s_ashr_i32 s1, s0, 31
	s_abs_i32 s0, s0
	v_cmp_lt_i32_e32 vcc, v176, v177
	v_mul_f32_e32 v5, 0x4f7ffffe, v5
	v_cvt_u32_f32_e32 v5, v5
	v_cndmask_b32_e32 v22, v175, v176, vcc
	v_readfirstlane_b32 s9, v5
	s_mul_i32 s8, s8, s9
	s_mul_hi_u32 s8, s9, s8
	s_add_i32 s9, s9, s8
	s_mul_hi_u32 s8, s0, s9
	s_mul_i32 s8, s8, s5
	s_sub_i32 s0, s0, s8
	s_sub_i32 s8, s0, s5
	s_cmp_ge_u32 s0, s5
	s_cselect_b32 s0, s8, s0
	s_sub_i32 s8, s0, s5
	s_cmp_ge_u32 s0, s5
	s_cselect_b32 s0, s8, s0
	s_xor_b32 s0, s0, s1
	s_sub_i32 s0, s0, s1
	s_add_i32 s4, s4, s0
	s_waitcnt lgkmcnt(0)
	v_lshl_add_u32 v6, s4, 8, v173
	v_ashrrev_i32_e32 v7, 31, v6
	v_lshlrev_b64 v[6:7], 7, v[6:7]
	v_lshl_add_u64 v[18:19], v[128:129], 0, v[6:7]
	global_load_dwordx4 v[56:59], v[18:19], off
	global_load_dwordx4 v[60:63], v[18:19], off offset:16
	global_load_dwordx4 v[64:67], v[18:19], off offset:32
	s_nop 0
	global_load_dwordx4 v[68:71], v[18:19], off offset:48
	v_readlane_b32 s0, v236, 0
	s_add_u32 s2, s2, s0
	v_readlane_b32 s0, v236, 1
	s_addc_u32 s3, s3, s0
	s_add_u32 s11, s11, 1
	v_cmp_gt_i64_e32 vcc, s[2:3], v[0:1]
	s_cbranch_vccnz .Lfill1_p2
; #define PG8_LAS __attribute__((address_space(3)))
;     __host__ __device__ bool next(int i, Unit& u) const {
;         const long L = (long)i * G + c; if (L >= nwg) return false;
;         int wgid = (int)L; { const int q = nwg / NXCD, r = nwg % NXCD, xcd = wgid % NXCD, off = wgid / NXCD; wgid = (xcd < r ? xcd * (q + 1) : r * (q + 1) + (xcd - r) * q) + off; }
;         const int nig = WGM * nN, gid = wgid / nig, fm = gid * WGM, gsz = (nM - fm) < WGM ? (nM - fm) : WGM;
;         u.pm = fm + ((wgid % nig) % gsz); u.pn = (wgid % nig) / gsz; return true;
; template <class Sched> __device__ __forceinline__ void fill_rstd_table(PG8_LAS float* tab, const float* ssq, const Sched& S) {
;     const int tid = threadIdx.x, r = tid >> 1, hf = tid & 1; Unit u;
;     for (int i = 0; S.next(i, u); ++i) { const f32x4* p = (const f32x4*)(ssq + (size_t)(u.pm * BM + r) * 32 + hf * 16); float s = 0.f;
; #pragma unroll
;         for (int j = 0; j < 4; ++j) { const f32x4 a = p[j]; s += (a[0] + a[1]) + (a[2] + a[3]); }
	s_ashr_i32 s0, s2, 31
	s_lshr_b32 s0, s0, 29
	s_add_i32 s0, s2, s0
	s_ashr_i32 s1, s0, 3
	s_and_b32 s0, s0, -8
	s_sub_i32 s0, s2, s0
	s_cmp_lt_i32 s0, 0
	s_cselect_b32 s4, s6, 0xb0
	s_mul_i32 s0, s0, s4
	s_add_i32 s0, s0, s1
	s_mul_hi_i32 s1, s0, 0x2e8ba2e9
	s_lshr_b32 s4, s1, 31
	s_ashr_i32 s1, s1, 6
	s_add_i32 s1, s1, s4
	s_lshl_b32 s4, s1, 3
	s_sub_i32 s5, 32, s4
	s_min_i32 s5, s5, 8
	s_abs_i32 s5, s5
	v_cvt_f32_u32_e32 v5, s5
	s_sub_i32 s8, 0, s5
	s_mulk_i32 s1, 0x160
	s_sub_i32 s0, s0, s1
	v_rcp_iflag_f32_e32 v5, v5
	s_ashr_i32 s1, s0, 31
	s_abs_i32 s0, s0
	v_cmp_lt_i32_e32 vcc, v176, v177
	v_mul_f32_e32 v5, 0x4f7ffffe, v5
	v_cvt_u32_f32_e32 v5, v5
	v_cndmask_b32_e32 v22, v175, v176, vcc
	v_readfirstlane_b32 s9, v5
	s_mul_i32 s8, s8, s9
	s_mul_hi_u32 s8, s9, s8
	s_add_i32 s9, s9, s8
	s_mul_hi_u32 s8, s0, s9
	s_mul_i32 s8, s8, s5
	s_sub_i32 s0, s0, s8
	s_sub_i32 s8, s0, s5
	s_cmp_ge_u32 s0, s5
	s_cselect_b32 s0, s8, s0
	s_sub_i32 s8, s0, s5
	s_cmp_ge_u32 s0, s5
	s_cselect_b32 s0, s8, s0
	s_xor_b32 s0, s0, s1
	s_sub_i32 s0, s0, s1
	s_add_i32 s4, s4, s0
	s_waitcnt lgkmcnt(0)
	v_lshl_add_u32 v6, s4, 8, v173
	v_ashrrev_i32_e32 v7, 31, v6
	v_lshlrev_b64 v[6:7], 7, v[6:7]
	v_lshl_add_u64 v[18:19], v[128:129], 0, v[6:7]
	global_load_dwordx4 v[132:135], v[18:19], off
	global_load_dwordx4 v[136:139], v[18:19], off offset:16
	global_load_dwordx4 v[140:143], v[18:19], off offset:32
	s_nop 0
	global_load_dwordx4 v[144:147], v[18:19], off offset:48
	v_readlane_b32 s0, v236, 0
	s_add_u32 s2, s2, s0
	v_readlane_b32 s0, v236, 1
	s_addc_u32 s3, s3, s0
	s_add_u32 s11, s11, 1
	v_cmp_gt_i64_e32 vcc, s[2:3], v[0:1]
	s_cbranch_vccnz .Lfill1_p2
	s_ashr_i32 s0, s2, 31
	s_lshr_b32 s0, s0, 29
	s_add_i32 s0, s2, s0
	s_ashr_i32 s1, s0, 3
	s_and_b32 s0, s0, -8
	s_sub_i32 s0, s2, s0
	s_cmp_lt_i32 s0, 0
	s_cselect_b32 s4, s6, 0xb0
	s_mul_i32 s0, s0, s4
	s_add_i32 s0, s0, s1
	s_mul_hi_i32 s1, s0, 0x2e8ba2e9
	s_lshr_b32 s4, s1, 31
	s_ashr_i32 s1, s1, 6
	s_add_i32 s1, s1, s4
	s_lshl_b32 s4, s1, 3
	s_sub_i32 s5, 32, s4
	s_min_i32 s5, s5, 8
	s_abs_i32 s5, s5
	v_cvt_f32_u32_e32 v5, s5
	s_sub_i32 s8, 0, s5
	s_mulk_i32 s1, 0x160
	s_sub_i32 s0, s0, s1
	v_rcp_iflag_f32_e32 v5, v5
	s_ashr_i32 s1, s0, 31
	s_abs_i32 s0, s0
	v_cmp_lt_i32_e32 vcc, v176, v177
	v_mul_f32_e32 v5, 0x4f7ffffe, v5
	v_cvt_u32_f32_e32 v5, v5
	v_cndmask_b32_e32 v22, v175, v176, vcc
	v_readfirstlane_b32 s9, v5
	s_mul_i32 s8, s8, s9
	s_mul_hi_u32 s8, s9, s8
	s_add_i32 s9, s9, s8
	s_mul_hi_u32 s8, s0, s9
	s_mul_i32 s8, s8, s5
	s_sub_i32 s0, s0, s8
	s_sub_i32 s8, s0, s5
	s_cmp_ge_u32 s0, s5
	s_cselect_b32 s0, s8, s0
	s_sub_i32 s8, s0, s5
	s_cmp_ge_u32 s0, s5
	s_cselect_b32 s0, s8, s0
	s_xor_b32 s0, s0, s1
	s_sub_i32 s0, s0, s1
	s_add_i32 s4, s4, s0
	s_waitcnt lgkmcnt(0)
	v_lshl_add_u32 v6, s4, 8, v173
	v_ashrrev_i32_e32 v7, 31, v6
	v_lshlrev_b64 v[6:7], 7, v[6:7]
	v_lshl_add_u64 v[18:19], v[128:129], 0, v[6:7]
	global_load_dwordx4 v[148:151], v[18:19], off
	global_load_dwordx4 v[152:155], v[18:19], off offset:16
	global_load_dwordx4 v[156:159], v[18:19], off offset:32
	s_nop 0
	global_load_dwordx4 v[160:163], v[18:19], off offset:48
	v_readlane_b32 s0, v236, 0
	s_add_u32 s2, s2, s0
	v_readlane_b32 s0, v236, 1
	s_addc_u32 s3, s3, s0
	s_add_u32 s11, s11, 1
	v_cmp_gt_i64_e32 vcc, s[2:3], v[0:1]
	s_cbranch_vccnz .Lfill1_p2
	s_ashr_i32 s0, s2, 31
	s_lshr_b32 s0, s0, 29
	s_add_i32 s0, s2, s0
	s_ashr_i32 s1, s0, 3
	s_and_b32 s0, s0, -8
	s_sub_i32 s0, s2, s0
	s_cmp_lt_i32 s0, 0
	s_cselect_b32 s4, s6, 0xb0
	s_mul_i32 s0, s0, s4
	s_add_i32 s0, s0, s1
	s_mul_hi_i32 s1, s0, 0x2e8ba2e9
	s_lshr_b32 s4, s1, 31
	s_ashr_i32 s1, s1, 6
	s_add_i32 s1, s1, s4
	s_lshl_b32 s4, s1, 3
	s_sub_i32 s5, 32, s4
	s_min_i32 s5, s5, 8
	s_abs_i32 s5, s5
	v_cvt_f32_u32_e32 v5, s5
	s_sub_i32 s8, 0, s5
	s_mulk_i32 s1, 0x160
	s_sub_i32 s0, s0, s1
	v_rcp_iflag_f32_e32 v5, v5
	s_ashr_i32 s1, s0, 31
	s_abs_i32 s0, s0
	v_cmp_lt_i32_e32 vcc, v176, v177
	v_mul_f32_e32 v5, 0x4f7ffffe, v5
	v_cvt_u32_f32_e32 v5, v5
	v_cndmask_b32_e32 v22, v175, v176, vcc
	v_readfirstlane_b32 s9, v5
	s_mul_i32 s8, s8, s9
	s_mul_hi_u32 s8, s9, s8
	s_add_i32 s9, s9, s8
	s_mul_hi_u32 s8, s0, s9
	s_mul_i32 s8, s8, s5
	s_sub_i32 s0, s0, s8
	s_sub_i32 s8, s0, s5
	s_cmp_ge_u32 s0, s5
	s_cselect_b32 s0, s8, s0
	s_sub_i32 s8, s0, s5
	s_cmp_ge_u32 s0, s5
	s_cselect_b32 s0, s8, s0
	s_xor_b32 s0, s0, s1
	s_sub_i32 s0, s0, s1
	s_add_i32 s4, s4, s0
	s_waitcnt lgkmcnt(0)
	v_lshl_add_u32 v6, s4, 8, v173
	v_ashrrev_i32_e32 v7, 31, v6
	v_lshlrev_b64 v[6:7], 7, v[6:7]
	v_lshl_add_u64 v[18:19], v[128:129], 0, v[6:7]
	global_load_dwordx4 v[180:183], v[18:19], off
	global_load_dwordx4 v[184:187], v[18:19], off offset:16
	global_load_dwordx4 v[188:191], v[18:19], off offset:32
	s_nop 0
	global_load_dwordx4 v[192:195], v[18:19], off offset:48
	v_readlane_b32 s0, v236, 0
	s_add_u32 s2, s2, s0
	v_readlane_b32 s0, v236, 1
	s_addc_u32 s3, s3, s0
	s_add_u32 s11, s11, 1
; template <class Sched> __device__ __forceinline__ void fill_rstd_table(PG8_LAS float* tab, const float* ssq, const Sched& S) {
;     ...
;     for (int i = 0; S.next(i, u); ++i) { const f32x4* p = (const f32x4*)(ssq + (size_t)(u.pm * BM + r) * 32 + hf * 16); float s = 0.f;
; #pragma unroll
;         for (int j = 0; j < 4; ++j) { const f32x4 a = p[j]; s += (a[0] + a[1]) + (a[2] + a[3]); }
;         s += __shfl_xor(s, 1);
;         if (hf == 0) tab[i * 256 + r] = 1.0f / sqrtf(s * (1.0f / 2048.0f) + RMS_EPS); }
.Lfill1_p2:
	s_waitcnt vmcnt(0)
	s_cmp_le_u32 s11, 0
	s_cbranch_scc1 .Lfill1_done
	v_mov_b32_e32 v6, v24
	v_mov_b32_e32 v7, v25
	v_mov_b32_e32 v8, v26
	v_mov_b32_e32 v9, v27
	v_mov_b32_e32 v10, v28
	v_mov_b32_e32 v11, v29
	v_mov_b32_e32 v12, v30
	v_mov_b32_e32 v13, v31
	v_mov_b32_e32 v14, v32
	v_mov_b32_e32 v15, v33
	v_mov_b32_e32 v16, v34
	v_mov_b32_e32 v17, v35
	v_mov_b32_e32 v18, v36
	v_mov_b32_e32 v19, v37
	v_mov_b32_e32 v20, v38
	v_mov_b32_e32 v21, v39
	v_add_f32_e32 v5, v6, v7
	v_add_f32_e32 v6, v8, v9
	v_add_f32_e32 v7, v10, v11
	v_add_f32_e32 v8, v12, v13
	v_add_f32_e32 v5, v5, v6
	v_add_f32_e32 v9, v14, v15
	v_add_f32_e32 v10, v16, v17
	v_add_f32_e32 v6, v7, v8
	v_add_f32_e32 v5, 0, v5
	v_add_f32_e32 v11, v18, v19
	v_add_f32_e32 v12, v20, v21
	v_add_f32_e32 v7, v9, v10
	v_add_f32_e32 v5, v5, v6
	v_add_f32_e32 v8, v11, v12
	v_add_f32_e32 v5, v5, v7
	v_add_f32_e32 v5, v5, v8
	v_lshlrev_b32_e32 v6, 2, v22
	ds_bpermute_b32 v6, v6, v5
	s_mov_b64 s[4:5], exec
	v_readlane_b32 s0, v237, 50
	v_readlane_b32 s1, v237, 51
	s_and_b64 s[0:1], s[4:5], s[0:1]
	s_mov_b64 exec, s[0:1]
	s_cbranch_execz .Lfill1_j0
	s_waitcnt lgkmcnt(0)
	v_add_f32_e32 v5, v5, v6
	v_fmamk_f32 v5, v5, 0x3a000000, v2
	v_mul_f32_e32 v6, 0x4f800000, v5
	v_cmp_gt_f32_e32 vcc, s7, v5
	s_nop 1
	v_cndmask_b32_e32 v5, v5, v6, vcc
	v_sqrt_f32_e32 v6, v5
	s_nop 0
	v_add_u32_e32 v7, -1, v6
	v_fma_f32 v9, -v7, v6, v5
	v_add_u32_e32 v8, 1, v6
	v_cmp_ge_f32_e64 s[0:1], 0, v9
	s_nop 1
	v_cndmask_b32_e64 v7, v6, v7, s[0:1]
	v_fma_f32 v6, -v8, v6, v5
	v_cmp_lt_f32_e64 s[0:1], 0, v6
	s_nop 1
	v_cndmask_b32_e64 v6, v7, v8, s[0:1]
	v_mul_f32_e32 v7, 0x37800000, v6
	v_cndmask_b32_e32 v6, v6, v7, vcc
	v_cmp_class_f32_e32 vcc, v5, v3
	s_nop 1
	v_cndmask_b32_e32 v5, v6, v5, vcc
	v_div_scale_f32 v6, s[0:1], v5, v5, 1.0
	v_rcp_f32_e32 v7, v6
	s_nop 0
	v_fma_f32 v8, -v6, v7, 1.0
	v_fmac_f32_e32 v7, v8, v7
	v_div_scale_f32 v8, vcc, 1.0, v5, 1.0
	v_mul_f32_e32 v9, v8, v7
	v_fma_f32 v10, -v6, v9, v8
	v_fmac_f32_e32 v9, v10, v7
	v_fma_f32 v6, -v6, v9, v8
	v_div_fmas_f32 v6, v6, v7, v9
	v_div_fixup_f32 v5, v6, v5, 1.0
	ds_write_b32 v4, v5
.Lfill1_j0:
	s_or_b64 exec, exec, s[4:5]
	v_add_u32_e32 v4, 0x400, v4
	s_cmp_le_u32 s11, 1
	s_cbranch_scc1 .Lfill1_done
	v_mov_b32_e32 v6, v40
	v_mov_b32_e32 v7, v41
	v_mov_b32_e32 v8, v42
	v_mov_b32_e32 v9, v43
	v_mov_b32_e32 v10, v44
	v_mov_b32_e32 v11, v45
	v_mov_b32_e32 v12, v46
	v_mov_b32_e32 v13, v47
	v_mov_b32_e32 v14, v48
	v_mov_b32_e32 v15, v49
	v_mov_b32_e32 v16, v50
	v_mov_b32_e32 v17, v51
	v_mov_b32_e32 v18, v52
	v_mov_b32_e32 v19, v53
	v_mov_b32_e32 v20, v54
	v_mov_b32_e32 v21, v55
	v_add_f32_e32 v5, v6, v7
	v_add_f32_e32 v6, v8, v9
	v_add_f32_e32 v7, v10, v11
	v_add_f32_e32 v8, v12, v13
	v_add_f32_e32 v5, v5, v6
	v_add_f32_e32 v9, v14, v15
	v_add_f32_e32 v10, v16, v17
	v_add_f32_e32 v6, v7, v8
	v_add_f32_e32 v5, 0, v5
	v_add_f32_e32 v11, v18, v19
	v_add_f32_e32 v12, v20, v21
	v_add_f32_e32 v7, v9, v10
	v_add_f32_e32 v5, v5, v6
	v_add_f32_e32 v8, v11, v12
	v_add_f32_e32 v5, v5, v7
	v_add_f32_e32 v5, v5, v8
	v_lshlrev_b32_e32 v6, 2, v22
	ds_bpermute_b32 v6, v6, v5
	s_mov_b64 s[4:5], exec
	v_readlane_b32 s0, v237, 50
	v_readlane_b32 s1, v237, 51
	s_and_b64 s[0:1], s[4:5], s[0:1]
	s_mov_b64 exec, s[0:1]
	s_cbranch_execz .Lfill1_j1
	s_waitcnt lgkmcnt(0)
	v_add_f32_e32 v5, v5, v6
	v_fmamk_f32 v5, v5, 0x3a000000, v2
	v_mul_f32_e32 v6, 0x4f800000, v5
	v_cmp_gt_f32_e32 vcc, s7, v5
	s_nop 1
	v_cndmask_b32_e32 v5, v5, v6, vcc
	v_sqrt_f32_e32 v6, v5
	s_nop 0
	v_add_u32_e32 v7, -1, v6
	v_fma_f32 v9, -v7, v6, v5
	v_add_u32_e32 v8, 1, v6
	v_cmp_ge_f32_e64 s[0:1], 0, v9
	s_nop 1
	v_cndmask_b32_e64 v7, v6, v7, s[0:1]
	v_fma_f32 v6, -v8, v6, v5
	v_cmp_lt_f32_e64 s[0:1], 0, v6
	s_nop 1
	v_cndmask_b32_e64 v6, v7, v8, s[0:1]
	v_mul_f32_e32 v7, 0x37800000, v6
	v_cndmask_b32_e32 v6, v6, v7, vcc
	v_cmp_class_f32_e32 vcc, v5, v3
	s_nop 1
	v_cndmask_b32_e32 v5, v6, v5, vcc
	v_div_scale_f32 v6, s[0:1], v5, v5, 1.0
	v_rcp_f32_e32 v7, v6
	s_nop 0
	v_fma_f32 v8, -v6, v7, 1.0
	v_fmac_f32_e32 v7, v8, v7
	v_div_scale_f32 v8, vcc, 1.0, v5, 1.0
	v_mul_f32_e32 v9, v8, v7
	v_fma_f32 v10, -v6, v9, v8
	v_fmac_f32_e32 v9, v10, v7
	v_fma_f32 v6, -v6, v9, v8
	v_div_fmas_f32 v6, v6, v7, v9
	v_div_fixup_f32 v5, v6, v5, 1.0
	ds_write_b32 v4, v5
.Lfill1_j1:
	s_or_b64 exec, exec, s[4:5]
	v_add_u32_e32 v4, 0x400, v4
	s_cmp_le_u32 s11, 2
	s_cbranch_scc1 .Lfill1_done
	v_mov_b32_e32 v6, v56
	v_mov_b32_e32 v7, v57
	v_mov_b32_e32 v8, v58
	v_mov_b32_e32 v9, v59
	v_mov_b32_e32 v10, v60
	v_mov_b32_e32 v11, v61
	v_mov_b32_e32 v12, v62
	v_mov_b32_e32 v13, v63
	v_mov_b32_e32 v14, v64
	v_mov_b32_e32 v15, v65
	v_mov_b32_e32 v16, v66
	v_mov_b32_e32 v17, v67
	v_mov_b32_e32 v18, v68
	v_mov_b32_e32 v19, v69
	v_mov_b32_e32 v20, v70
	v_mov_b32_e32 v21, v71
	v_add_f32_e32 v5, v6, v7
	v_add_f32_e32 v6, v8, v9
	v_add_f32_e32 v7, v10, v11
	v_add_f32_e32 v8, v12, v13
	v_add_f32_e32 v5, v5, v6
	v_add_f32_e32 v9, v14, v15
	v_add_f32_e32 v10, v16, v17
	v_add_f32_e32 v6, v7, v8
	v_add_f32_e32 v5, 0, v5
	v_add_f32_e32 v11, v18, v19
	v_add_f32_e32 v12, v20, v21
	v_add_f32_e32 v7, v9, v10
	v_add_f32_e32 v5, v5, v6
	v_add_f32_e32 v8, v11, v12
	v_add_f32_e32 v5, v5, v7
	v_add_f32_e32 v5, v5, v8
	v_lshlrev_b32_e32 v6, 2, v22
	ds_bpermute_b32 v6, v6, v5
	s_mov_b64 s[4:5], exec
	v_readlane_b32 s0, v237, 50
	v_readlane_b32 s1, v237, 51
	s_and_b64 s[0:1], s[4:5], s[0:1]
	s_mov_b64 exec, s[0:1]
	s_cbranch_execz .Lfill1_j2
	s_waitcnt lgkmcnt(0)
	v_add_f32_e32 v5, v5, v6
	v_fmamk_f32 v5, v5, 0x3a000000, v2
	v_mul_f32_e32 v6, 0x4f800000, v5
	v_cmp_gt_f32_e32 vcc, s7, v5
	s_nop 1
	v_cndmask_b32_e32 v5, v5, v6, vcc
	v_sqrt_f32_e32 v6, v5
	s_nop 0
	v_add_u32_e32 v7, -1, v6
	v_fma_f32 v9, -v7, v6, v5
	v_add_u32_e32 v8, 1, v6
	v_cmp_ge_f32_e64 s[0:1], 0, v9
	s_nop 1
	v_cndmask_b32_e64 v7, v6, v7, s[0:1]
	v_fma_f32 v6, -v8, v6, v5
	v_cmp_lt_f32_e64 s[0:1], 0, v6
	s_nop 1
	v_cndmask_b32_e64 v6, v7, v8, s[0:1]
	v_mul_f32_e32 v7, 0x37800000, v6
	v_cndmask_b32_e32 v6, v6, v7, vcc
	v_cmp_class_f32_e32 vcc, v5, v3
	s_nop 1
	v_cndmask_b32_e32 v5, v6, v5, vcc
	v_div_scale_f32 v6, s[0:1], v5, v5, 1.0
	v_rcp_f32_e32 v7, v6
	s_nop 0
	v_fma_f32 v8, -v6, v7, 1.0
	v_fmac_f32_e32 v7, v8, v7
	v_div_scale_f32 v8, vcc, 1.0, v5, 1.0
	v_mul_f32_e32 v9, v8, v7
	v_fma_f32 v10, -v6, v9, v8
	v_fmac_f32_e32 v9, v10, v7
	v_fma_f32 v6, -v6, v9, v8
	v_div_fmas_f32 v6, v6, v7, v9
	v_div_fixup_f32 v5, v6, v5, 1.0
	ds_write_b32 v4, v5
; template <class Sched> __device__ __forceinline__ void fill_rstd_table(PG8_LAS float* tab, const float* ssq, const Sched& S) {
;     ...
;     for (int i = 0; S.next(i, u); ++i) { const f32x4* p = (const f32x4*)(ssq + (size_t)(u.pm * BM + r) * 32 + hf * 16); float s = 0.f;
; #pragma unroll
;         for (int j = 0; j < 4; ++j) { const f32x4 a = p[j]; s += (a[0] + a[1]) + (a[2] + a[3]); }
;         s += __shfl_xor(s, 1);
;         if (hf == 0) tab[i * 256 + r] = 1.0f / sqrtf(s * (1.0f / 2048.0f) + RMS_EPS); }
.Lfill1_j2:
	s_or_b64 exec, exec, s[4:5]
	v_add_u32_e32 v4, 0x400, v4
	s_cmp_le_u32 s11, 3
	s_cbranch_scc1 .Lfill1_done
	v_mov_b32_e32 v6, v132
	v_mov_b32_e32 v7, v133
	v_mov_b32_e32 v8, v134
	v_mov_b32_e32 v9, v135
	v_mov_b32_e32 v10, v136
	v_mov_b32_e32 v11, v137
	v_mov_b32_e32 v12, v138
	v_mov_b32_e32 v13, v139
	v_mov_b32_e32 v14, v140
	v_mov_b32_e32 v15, v141
	v_mov_b32_e32 v16, v142
	v_mov_b32_e32 v17, v143
	v_mov_b32_e32 v18, v144
	v_mov_b32_e32 v19, v145
	v_mov_b32_e32 v20, v146
	v_mov_b32_e32 v21, v147
	v_add_f32_e32 v5, v6, v7
	v_add_f32_e32 v6, v8, v9
	v_add_f32_e32 v7, v10, v11
	v_add_f32_e32 v8, v12, v13
	v_add_f32_e32 v5, v5, v6
	v_add_f32_e32 v9, v14, v15
	v_add_f32_e32 v10, v16, v17
	v_add_f32_e32 v6, v7, v8
	v_add_f32_e32 v5, 0, v5
	v_add_f32_e32 v11, v18, v19
	v_add_f32_e32 v12, v20, v21
	v_add_f32_e32 v7, v9, v10
	v_add_f32_e32 v5, v5, v6
	v_add_f32_e32 v8, v11, v12
	v_add_f32_e32 v5, v5, v7
	v_add_f32_e32 v5, v5, v8
	v_lshlrev_b32_e32 v6, 2, v22
	ds_bpermute_b32 v6, v6, v5
	s_mov_b64 s[4:5], exec
	v_readlane_b32 s0, v237, 50
	v_readlane_b32 s1, v237, 51
	s_and_b64 s[0:1], s[4:5], s[0:1]
	s_mov_b64 exec, s[0:1]
	s_cbranch_execz .Lfill1_j3
	s_waitcnt lgkmcnt(0)
	v_add_f32_e32 v5, v5, v6
	v_fmamk_f32 v5, v5, 0x3a000000, v2
	v_mul_f32_e32 v6, 0x4f800000, v5
	v_cmp_gt_f32_e32 vcc, s7, v5
	s_nop 1
	v_cndmask_b32_e32 v5, v5, v6, vcc
	v_sqrt_f32_e32 v6, v5
	s_nop 0
	v_add_u32_e32 v7, -1, v6
	v_fma_f32 v9, -v7, v6, v5
	v_add_u32_e32 v8, 1, v6
	v_cmp_ge_f32_e64 s[0:1], 0, v9
	s_nop 1
	v_cndmask_b32_e64 v7, v6, v7, s[0:1]
	v_fma_f32 v6, -v8, v6, v5
	v_cmp_lt_f32_e64 s[0:1], 0, v6
	s_nop 1
	v_cndmask_b32_e64 v6, v7, v8, s[0:1]
	v_mul_f32_e32 v7, 0x37800000, v6
	v_cndmask_b32_e32 v6, v6, v7, vcc
	v_cmp_class_f32_e32 vcc, v5, v3
	s_nop 1
	v_cndmask_b32_e32 v5, v6, v5, vcc
	v_div_scale_f32 v6, s[0:1], v5, v5, 1.0
	v_rcp_f32_e32 v7, v6
	s_nop 0
	v_fma_f32 v8, -v6, v7, 1.0
	v_fmac_f32_e32 v7, v8, v7
	v_div_scale_f32 v8, vcc, 1.0, v5, 1.0
	v_mul_f32_e32 v9, v8, v7
	v_fma_f32 v10, -v6, v9, v8
	v_fmac_f32_e32 v9, v10, v7
	v_fma_f32 v6, -v6, v9, v8
	v_div_fmas_f32 v6, v6, v7, v9
	v_div_fixup_f32 v5, v6, v5, 1.0
	ds_write_b32 v4, v5
.Lfill1_j3:
	s_or_b64 exec, exec, s[4:5]
	v_add_u32_e32 v4, 0x400, v4
	s_cmp_le_u32 s11, 4
	s_cbranch_scc1 .Lfill1_done
	v_mov_b32_e32 v6, v148
	v_mov_b32_e32 v7, v149
	v_mov_b32_e32 v8, v150
	v_mov_b32_e32 v9, v151
	v_mov_b32_e32 v10, v152
	v_mov_b32_e32 v11, v153
	v_mov_b32_e32 v12, v154
	v_mov_b32_e32 v13, v155
	v_mov_b32_e32 v14, v156
	v_mov_b32_e32 v15, v157
	v_mov_b32_e32 v16, v158
	v_mov_b32_e32 v17, v159
	v_mov_b32_e32 v18, v160
	v_mov_b32_e32 v19, v161
	v_mov_b32_e32 v20, v162
	v_mov_b32_e32 v21, v163
	v_add_f32_e32 v5, v6, v7
	v_add_f32_e32 v6, v8, v9
	v_add_f32_e32 v7, v10, v11
	v_add_f32_e32 v8, v12, v13
	v_add_f32_e32 v5, v5, v6
	v_add_f32_e32 v9, v14, v15
	v_add_f32_e32 v10, v16, v17
	v_add_f32_e32 v6, v7, v8
	v_add_f32_e32 v5, 0, v5
	v_add_f32_e32 v11, v18, v19
	v_add_f32_e32 v12, v20, v21
	v_add_f32_e32 v7, v9, v10
	v_add_f32_e32 v5, v5, v6
	v_add_f32_e32 v8, v11, v12
	v_add_f32_e32 v5, v5, v7
	v_add_f32_e32 v5, v5, v8
	v_lshlrev_b32_e32 v6, 2, v22
	ds_bpermute_b32 v6, v6, v5
	s_mov_b64 s[4:5], exec
	v_readlane_b32 s0, v237, 50
	v_readlane_b32 s1, v237, 51
	s_and_b64 s[0:1], s[4:5], s[0:1]
	s_mov_b64 exec, s[0:1]
	s_cbranch_execz .Lfill1_j4
	s_waitcnt lgkmcnt(0)
	v_add_f32_e32 v5, v5, v6
	v_fmamk_f32 v5, v5, 0x3a000000, v2
	v_mul_f32_e32 v6, 0x4f800000, v5
	v_cmp_gt_f32_e32 vcc, s7, v5
	s_nop 1
	v_cndmask_b32_e32 v5, v5, v6, vcc
	v_sqrt_f32_e32 v6, v5
	s_nop 0
	v_add_u32_e32 v7, -1, v6
	v_fma_f32 v9, -v7, v6, v5
	v_add_u32_e32 v8, 1, v6
	v_cmp_ge_f32_e64 s[0:1], 0, v9
	s_nop 1
	v_cndmask_b32_e64 v7, v6, v7, s[0:1]
	v_fma_f32 v6, -v8, v6, v5
	v_cmp_lt_f32_e64 s[0:1], 0, v6
	s_nop 1
	v_cndmask_b32_e64 v6, v7, v8, s[0:1]
	v_mul_f32_e32 v7, 0x37800000, v6
	v_cndmask_b32_e32 v6, v6, v7, vcc
	v_cmp_class_f32_e32 vcc, v5, v3
	s_nop 1
	v_cndmask_b32_e32 v5, v6, v5, vcc
	v_div_scale_f32 v6, s[0:1], v5, v5, 1.0
	v_rcp_f32_e32 v7, v6
	s_nop 0
	v_fma_f32 v8, -v6, v7, 1.0
	v_fmac_f32_e32 v7, v8, v7
	v_div_scale_f32 v8, vcc, 1.0, v5, 1.0
	v_mul_f32_e32 v9, v8, v7
	v_fma_f32 v10, -v6, v9, v8
	v_fmac_f32_e32 v9, v10, v7
	v_fma_f32 v6, -v6, v9, v8
	v_div_fmas_f32 v6, v6, v7, v9
	v_div_fixup_f32 v5, v6, v5, 1.0
	ds_write_b32 v4, v5
.Lfill1_j4:
	s_or_b64 exec, exec, s[4:5]
	v_add_u32_e32 v4, 0x400, v4
	s_cmp_le_u32 s11, 5
	s_cbranch_scc1 .Lfill1_done
	v_mov_b32_e32 v6, v180
	v_mov_b32_e32 v7, v181
	v_mov_b32_e32 v8, v182
	v_mov_b32_e32 v9, v183
	v_mov_b32_e32 v10, v184
	v_mov_b32_e32 v11, v185
	v_mov_b32_e32 v12, v186
	v_mov_b32_e32 v13, v187
	v_mov_b32_e32 v14, v188
	v_mov_b32_e32 v15, v189
	v_mov_b32_e32 v16, v190
	v_mov_b32_e32 v17, v191
	v_mov_b32_e32 v18, v192
	v_mov_b32_e32 v19, v193
	v_mov_b32_e32 v20, v194
	v_mov_b32_e32 v21, v195
	v_add_f32_e32 v5, v6, v7
	v_add_f32_e32 v6, v8, v9
	v_add_f32_e32 v7, v10, v11
	v_add_f32_e32 v8, v12, v13
	v_add_f32_e32 v5, v5, v6
	v_add_f32_e32 v9, v14, v15
	v_add_f32_e32 v10, v16, v17
	v_add_f32_e32 v6, v7, v8
	v_add_f32_e32 v5, 0, v5
	v_add_f32_e32 v11, v18, v19
	v_add_f32_e32 v12, v20, v21
	v_add_f32_e32 v7, v9, v10
	v_add_f32_e32 v5, v5, v6
	v_add_f32_e32 v8, v11, v12
	v_add_f32_e32 v5, v5, v7
	v_add_f32_e32 v5, v5, v8
	v_lshlrev_b32_e32 v6, 2, v22
	ds_bpermute_b32 v6, v6, v5
	s_mov_b64 s[4:5], exec
	v_readlane_b32 s0, v237, 50
	v_readlane_b32 s1, v237, 51
	s_and_b64 s[0:1], s[4:5], s[0:1]
	s_mov_b64 exec, s[0:1]
	s_cbranch_execz .Lfill1_j5
	s_waitcnt lgkmcnt(0)
	v_add_f32_e32 v5, v5, v6
	v_fmamk_f32 v5, v5, 0x3a000000, v2
	v_mul_f32_e32 v6, 0x4f800000, v5
	v_cmp_gt_f32_e32 vcc, s7, v5
	s_nop 1
	v_cndmask_b32_e32 v5, v5, v6, vcc
	v_sqrt_f32_e32 v6, v5
	s_nop 0
	v_add_u32_e32 v7, -1, v6
	v_fma_f32 v9, -v7, v6, v5
	v_add_u32_e32 v8, 1, v6
	v_cmp_ge_f32_e64 s[0:1], 0, v9
	s_nop 1
	v_cndmask_b32_e64 v7, v6, v7, s[0:1]
	v_fma_f32 v6, -v8, v6, v5
	v_cmp_lt_f32_e64 s[0:1], 0, v6
	s_nop 1
	v_cndmask_b32_e64 v6, v7, v8, s[0:1]
	v_mul_f32_e32 v7, 0x37800000, v6
	v_cndmask_b32_e32 v6, v6, v7, vcc
	v_cmp_class_f32_e32 vcc, v5, v3
	s_nop 1
	v_cndmask_b32_e32 v5, v6, v5, vcc
	v_div_scale_f32 v6, s[0:1], v5, v5, 1.0
	v_rcp_f32_e32 v7, v6
	s_nop 0
	v_fma_f32 v8, -v6, v7, 1.0
	v_fmac_f32_e32 v7, v8, v7
	v_div_scale_f32 v8, vcc, 1.0, v5, 1.0
	v_mul_f32_e32 v9, v8, v7
	v_fma_f32 v10, -v6, v9, v8
	v_fmac_f32_e32 v9, v10, v7
	v_fma_f32 v6, -v6, v9, v8
	v_div_fmas_f32 v6, v6, v7, v9
	v_div_fixup_f32 v5, v6, v5, 1.0
	ds_write_b32 v4, v5

;     __host__ __device__ bool next(int i, Unit& u) const {
;         const long L = (long)i * G + c; if (L >= nwg) return false;
;         int wgid = (int)L; { const int q = nwg / NXCD, r = nwg % NXCD, xcd = wgid % NXCD, off = wgid / NXCD; wgid = (xcd < r ? xcd * (q + 1) : r * (q + 1) + (xcd - r) * q) + off; }
;         const int nig = WGM * nN, gid = wgid / nig, fm = gid * WGM, gsz = (nM - fm) < WGM ? (nM - fm) : WGM;
; template <class Sched> __device__ __forceinline__ void fill_rstd_table(PG8_LAS float* tab, const float* ssq, const Sched& S) {
;     ...
;     for (int i = 0; S.next(i, u); ++i) { const f32x4* p = (const f32x4*)(ssq + (size_t)(u.pm * BM + r) * 32 + hf * 16); float s = 0.f;
.LBB0_1154:
	s_or_b64 exec, exec, s[0:1]
	s_waitcnt lgkmcnt(0)
	v_mov_b64_e32 v[0:1], 0x3ff
	v_mov_b32_e32 v2, 0x358637bd
	s_mov_b32 s6, 0xf800000
	v_mov_b32_e32 v3, 0x260
	s_mov_b64 s[2:3], s[66:67]
	v_mov_b32_e32 v4, v174
	s_barrier
	s_waitcnt vmcnt(0)
	s_mov_b32 s9, 0
	v_cmp_gt_i64_e32 vcc, s[2:3], v[0:1]
	s_cbranch_vccnz .Lfill2_p2
	s_ashr_i32 s0, s2, 31
	s_lshr_b32 s0, s0, 29
	s_add_i32 s4, s2, s0
	s_and_b32 s0, s4, -8
	s_sub_i32 s5, s2, s0
	s_cmp_gt_i32 s5, -1
	s_mov_b64 s[0:1], -1
	s_cbranch_scc0 .Lfill2_a0_1160
	s_lshl_b32 s7, s5, 7
	s_mov_b64 s[0:1], 0

;     __host__ __device__ bool next(int i, Unit& u) const {
;     ...
;         int wgid = (int)L; { const int q = nwg / NXCD, r = nwg % NXCD, xcd = wgid % NXCD, off = wgid / NXCD; wgid = (xcd < r ? xcd * (q + 1) : r * (q + 1) + (xcd - r) * q) + off; }
;         const int nig = WGM * nN, gid = wgid / nig, fm = gid * WGM, gsz = (nM - fm) < WGM ? (nM - fm) : WGM;
;         u.pm = fm + ((wgid % nig) % gsz); u.pn = (wgid % nig) / gsz; return true;
; template <class Sched> __device__ __forceinline__ void fill_rstd_table(PG8_LAS float* tab, const float* ssq, const Sched& S) {
;     ...
;     for (int i = 0; S.next(i, u); ++i) { const f32x4* p = (const f32x4*)(ssq + (size_t)(u.pm * BM + r) * 32 + hf * 16); float s = 0.f;
; #pragma unroll
;         for (int j = 0; j < 4; ++j) { const f32x4 a = p[j]; s += (a[0] + a[1]) + (a[2] + a[3]); }
.Lfill2_a0_1162:
	s_ashr_i32 s0, s4, 3
	s_add_i32 s0, s7, s0
	s_ashr_i32 s1, s0, 31
	s_lshr_b32 s1, s1, 24
	s_add_i32 s1, s0, s1
	s_ashr_i32 s4, s1, 8
	s_lshl_b32 s4, s4, 3
	s_sub_i32 s5, 32, s4
	s_min_i32 s5, s5, 8
	s_abs_i32 s5, s5
	v_cvt_f32_u32_e32 v5, s5
	s_sub_i32 s7, 0, s5
	s_and_b32 s1, s1, 0xffffff00
	s_sub_i32 s0, s0, s1
	v_rcp_iflag_f32_e32 v5, v5
	s_ashr_i32 s1, s0, 31
	s_abs_i32 s0, s0
	v_cmp_lt_i32_e32 vcc, v176, v177
	v_mul_f32_e32 v5, 0x4f7ffffe, v5
	v_cvt_u32_f32_e32 v5, v5
	v_cndmask_b32_e32 v22, v175, v176, vcc
	v_readfirstlane_b32 s8, v5
	s_mul_i32 s7, s7, s8
	s_mul_hi_u32 s7, s8, s7
	s_add_i32 s8, s8, s7
	s_mul_hi_u32 s7, s0, s8
	s_mul_i32 s7, s7, s5
	s_sub_i32 s0, s0, s7
	s_sub_i32 s7, s0, s5
	s_cmp_ge_u32 s0, s5
	s_cselect_b32 s0, s7, s0
	s_sub_i32 s7, s0, s5
	s_cmp_ge_u32 s0, s5
	s_cselect_b32 s0, s7, s0
	s_xor_b32 s0, s0, s1
	s_sub_i32 s0, s0, s1
	s_add_i32 s4, s4, s0
	s_waitcnt lgkmcnt(0)
	v_lshl_add_u32 v6, s4, 8, v173
	v_ashrrev_i32_e32 v7, 31, v6
	v_lshlrev_b64 v[6:7], 7, v[6:7]
	v_lshl_add_u64 v[18:19], v[128:129], 0, v[6:7]
	global_load_dwordx4 v[24:27], v[18:19], off
	global_load_dwordx4 v[28:31], v[18:19], off offset:16
	global_load_dwordx4 v[32:35], v[18:19], off offset:32
	s_nop 0
	global_load_dwordx4 v[36:39], v[18:19], off offset:48
	v_readlane_b32 s0, v237, 47
	s_add_u32 s2, s2, s0
	v_readlane_b32 s0, v237, 46
	s_addc_u32 s3, s3, s0
	s_add_u32 s9, s9, 1
	v_cmp_gt_i64_e32 vcc, s[2:3], v[0:1]
	s_cbranch_vccnz .Lfill2_p2
	s_ashr_i32 s0, s2, 31
	s_lshr_b32 s0, s0, 29
	s_add_i32 s4, s2, s0
	s_and_b32 s0, s4, -8
	s_sub_i32 s5, s2, s0
	s_cmp_gt_i32 s5, -1
	s_mov_b64 s[0:1], -1
	s_cbranch_scc0 .Lfill2_a1_1160
	s_lshl_b32 s7, s5, 7
	s_mov_b64 s[0:1], 0

;     __host__ __device__ bool next(int i, Unit& u) const {
;     ...
;         int wgid = (int)L; { const int q = nwg / NXCD, r = nwg % NXCD, xcd = wgid % NXCD, off = wgid / NXCD; wgid = (xcd < r ? xcd * (q + 1) : r * (q + 1) + (xcd - r) * q) + off; }
;         const int nig = WGM * nN, gid = wgid / nig, fm = gid * WGM, gsz = (nM - fm) < WGM ? (nM - fm) : WGM;
;         u.pm = fm + ((wgid % nig) % gsz); u.pn = (wgid % nig) / gsz; return true;
; template <class Sched> __device__ __forceinline__ void fill_rstd_table(PG8_LAS float* tab, const float* ssq, const Sched& S) {
;     ...
;     for (int i = 0; S.next(i, u); ++i) { const f32x4* p = (const f32x4*)(ssq + (size_t)(u.pm * BM + r) * 32 + hf * 16); float s = 0.f;
; #pragma unroll
;         for (int j = 0; j < 4; ++j) { const f32x4 a = p[j]; s += (a[0] + a[1]) + (a[2] + a[3]); }
.Lfill2_a1_1162:
	s_ashr_i32 s0, s4, 3
	s_add_i32 s0, s7, s0
	s_ashr_i32 s1, s0, 31
	s_lshr_b32 s1, s1, 24
	s_add_i32 s1, s0, s1
	s_ashr_i32 s4, s1, 8
	s_lshl_b32 s4, s4, 3
	s_sub_i32 s5, 32, s4
	s_min_i32 s5, s5, 8
	s_abs_i32 s5, s5
	v_cvt_f32_u32_e32 v5, s5
	s_sub_i32 s7, 0, s5
	s_and_b32 s1, s1, 0xffffff00
	s_sub_i32 s0, s0, s1
	v_rcp_iflag_f32_e32 v5, v5
	s_ashr_i32 s1, s0, 31
	s_abs_i32 s0, s0
	v_cmp_lt_i32_e32 vcc, v176, v177
	v_mul_f32_e32 v5, 0x4f7ffffe, v5
	v_cvt_u32_f32_e32 v5, v5
	v_cndmask_b32_e32 v22, v175, v176, vcc
	v_readfirstlane_b32 s8, v5
	s_mul_i32 s7, s7, s8
	s_mul_hi_u32 s7, s8, s7
	s_add_i32 s8, s8, s7
	s_mul_hi_u32 s7, s0, s8
	s_mul_i32 s7, s7, s5
	s_sub_i32 s0, s0, s7
	s_sub_i32 s7, s0, s5
	s_cmp_ge_u32 s0, s5
	s_cselect_b32 s0, s7, s0
	s_sub_i32 s7, s0, s5
	s_cmp_ge_u32 s0, s5
	s_cselect_b32 s0, s7, s0
	s_xor_b32 s0, s0, s1
	s_sub_i32 s0, s0, s1
	s_add_i32 s4, s4, s0
	s_waitcnt lgkmcnt(0)
	v_lshl_add_u32 v6, s4, 8, v173
	v_ashrrev_i32_e32 v7, 31, v6
	v_lshlrev_b64 v[6:7], 7, v[6:7]
	v_lshl_add_u64 v[18:19], v[128:129], 0, v[6:7]
	global_load_dwordx4 v[40:43], v[18:19], off
	global_load_dwordx4 v[44:47], v[18:19], off offset:16
	global_load_dwordx4 v[48:51], v[18:19], off offset:32
	s_nop 0
	global_load_dwordx4 v[52:55], v[18:19], off offset:48
	v_readlane_b32 s0, v237, 47
	s_add_u32 s2, s2, s0
	v_readlane_b32 s0, v237, 46
	s_addc_u32 s3, s3, s0
	s_add_u32 s9, s9, 1
	v_cmp_gt_i64_e32 vcc, s[2:3], v[0:1]
	s_cbranch_vccnz .Lfill2_p2
	s_ashr_i32 s0, s2, 31
	s_lshr_b32 s0, s0, 29
	s_add_i32 s4, s2, s0
	s_and_b32 s0, s4, -8
	s_sub_i32 s5, s2, s0
	s_cmp_gt_i32 s5, -1
	s_mov_b64 s[0:1], -1
	s_cbranch_scc0 .Lfill2_a2_1160
	s_lshl_b32 s7, s5, 7
	s_mov_b64 s[0:1], 0

;     __host__ __device__ bool next(int i, Unit& u) const {
;     ...
;         int wgid = (int)L; { const int q = nwg / NXCD, r = nwg % NXCD, xcd = wgid % NXCD, off = wgid / NXCD; wgid = (xcd < r ? xcd * (q + 1) : r * (q + 1) + (xcd - r) * q) + off; }
;         const int nig = WGM * nN, gid = wgid / nig, fm = gid * WGM, gsz = (nM - fm) < WGM ? (nM - fm) : WGM;
;         u.pm = fm + ((wgid % nig) % gsz); u.pn = (wgid % nig) / gsz; return true;
; template <class Sched> __device__ __forceinline__ void fill_rstd_table(PG8_LAS float* tab, const float* ssq, const Sched& S) {
;     ...
;     for (int i = 0; S.next(i, u); ++i) { const f32x4* p = (const f32x4*)(ssq + (size_t)(u.pm * BM + r) * 32 + hf * 16); float s = 0.f;
; #pragma unroll
;         for (int j = 0; j < 4; ++j) { const f32x4 a = p[j]; s += (a[0] + a[1]) + (a[2] + a[3]); }
.Lfill2_a2_1162:
	s_ashr_i32 s0, s4, 3
	s_add_i32 s0, s7, s0
	s_ashr_i32 s1, s0, 31
	s_lshr_b32 s1, s1, 24
	s_add_i32 s1, s0, s1
	s_ashr_i32 s4, s1, 8
	s_lshl_b32 s4, s4, 3
	s_sub_i32 s5, 32, s4
	s_min_i32 s5, s5, 8
	s_abs_i32 s5, s5
	v_cvt_f32_u32_e32 v5, s5
	s_sub_i32 s7, 0, s5
	s_and_b32 s1, s1, 0xffffff00
	s_sub_i32 s0, s0, s1
	v_rcp_iflag_f32_e32 v5, v5
	s_ashr_i32 s1, s0, 31
	s_abs_i32 s0, s0
	v_cmp_lt_i32_e32 vcc, v176, v177
	v_mul_f32_e32 v5, 0x4f7ffffe, v5
	v_cvt_u32_f32_e32 v5, v5
	v_cndmask_b32_e32 v22, v175, v176, vcc
	v_readfirstlane_b32 s8, v5
	s_mul_i32 s7, s7, s8
	s_mul_hi_u32 s7, s8, s7
	s_add_i32 s8, s8, s7
	s_mul_hi_u32 s7, s0, s8
	s_mul_i32 s7, s7, s5
	s_sub_i32 s0, s0, s7
	s_sub_i32 s7, s0, s5
	s_cmp_ge_u32 s0, s5
	s_cselect_b32 s0, s7, s0
	s_sub_i32 s7, s0, s5
	s_cmp_ge_u32 s0, s5
	s_cselect_b32 s0, s7, s0
	s_xor_b32 s0, s0, s1
	s_sub_i32 s0, s0, s1
	s_add_i32 s4, s4, s0
	s_waitcnt lgkmcnt(0)
	v_lshl_add_u32 v6, s4, 8, v173
	v_ashrrev_i32_e32 v7, 31, v6
	v_lshlrev_b64 v[6:7], 7, v[6:7]
	v_lshl_add_u64 v[18:19], v[128:129], 0, v[6:7]
	global_load_dwordx4 v[56:59], v[18:19], off
	global_load_dwordx4 v[60:63], v[18:19], off offset:16
	global_load_dwordx4 v[64:67], v[18:19], off offset:32
	s_nop 0
	global_load_dwordx4 v[68:71], v[18:19], off offset:48
	v_readlane_b32 s0, v237, 47
	s_add_u32 s2, s2, s0
	v_readlane_b32 s0, v237, 46
	s_addc_u32 s3, s3, s0
	s_add_u32 s9, s9, 1
	v_cmp_gt_i64_e32 vcc, s[2:3], v[0:1]
	s_cbranch_vccnz .Lfill2_p2
	s_ashr_i32 s0, s2, 31
	s_lshr_b32 s0, s0, 29
	s_add_i32 s4, s2, s0
	s_and_b32 s0, s4, -8
	s_sub_i32 s5, s2, s0
	s_cmp_gt_i32 s5, -1
	s_mov_b64 s[0:1], -1
	s_cbranch_scc0 .Lfill2_a3_1160
	s_lshl_b32 s7, s5, 7
	s_mov_b64 s[0:1], 0

;     __host__ __device__ bool next(int i, Unit& u) const {
;     ...
;         int wgid = (int)L; { const int q = nwg / NXCD, r = nwg % NXCD, xcd = wgid % NXCD, off = wgid / NXCD; wgid = (xcd < r ? xcd * (q + 1) : r * (q + 1) + (xcd - r) * q) + off; }
;         const int nig = WGM * nN, gid = wgid / nig, fm = gid * WGM, gsz = (nM - fm) < WGM ? (nM - fm) : WGM;
;         u.pm = fm + ((wgid % nig) % gsz); u.pn = (wgid % nig) / gsz; return true;
; template <class Sched> __device__ __forceinline__ void fill_rstd_table(PG8_LAS float* tab, const float* ssq, const Sched& S) {
;     ...
;     for (int i = 0; S.next(i, u); ++i) { const f32x4* p = (const f32x4*)(ssq + (size_t)(u.pm * BM + r) * 32 + hf * 16); float s = 0.f;
; #pragma unroll
;         for (int j = 0; j < 4; ++j) { const f32x4 a = p[j]; s += (a[0] + a[1]) + (a[2] + a[3]); }
;         s += __shfl_xor(s, 1);
;         if (hf == 0) tab[i * 256 + r] = 1.0f / sqrtf(s * (1.0f / 2048.0f) + RMS_EPS); }
.Lfill2_a3_1162:
	s_ashr_i32 s0, s4, 3
	s_add_i32 s0, s7, s0
	s_ashr_i32 s1, s0, 31
	s_lshr_b32 s1, s1, 24
	s_add_i32 s1, s0, s1
	s_ashr_i32 s4, s1, 8
	s_lshl_b32 s4, s4, 3
	s_sub_i32 s5, 32, s4
	s_min_i32 s5, s5, 8
	s_abs_i32 s5, s5
	v_cvt_f32_u32_e32 v5, s5
	s_sub_i32 s7, 0, s5
	s_and_b32 s1, s1, 0xffffff00
	s_sub_i32 s0, s0, s1
	v_rcp_iflag_f32_e32 v5, v5
	s_ashr_i32 s1, s0, 31
	s_abs_i32 s0, s0
	v_cmp_lt_i32_e32 vcc, v176, v177
	v_mul_f32_e32 v5, 0x4f7ffffe, v5
	v_cvt_u32_f32_e32 v5, v5
	v_cndmask_b32_e32 v22, v175, v176, vcc
	v_readfirstlane_b32 s8, v5
	s_mul_i32 s7, s7, s8
	s_mul_hi_u32 s7, s8, s7
	s_add_i32 s8, s8, s7
	s_mul_hi_u32 s7, s0, s8
	s_mul_i32 s7, s7, s5
	s_sub_i32 s0, s0, s7
	s_sub_i32 s7, s0, s5
	s_cmp_ge_u32 s0, s5
	s_cselect_b32 s0, s7, s0
	s_sub_i32 s7, s0, s5
	s_cmp_ge_u32 s0, s5
	s_cselect_b32 s0, s7, s0
	s_xor_b32 s0, s0, s1
	s_sub_i32 s0, s0, s1
	s_add_i32 s4, s4, s0
	s_waitcnt lgkmcnt(0)
	v_lshl_add_u32 v6, s4, 8, v173
	v_ashrrev_i32_e32 v7, 31, v6
	v_lshlrev_b64 v[6:7], 7, v[6:7]
	v_lshl_add_u64 v[18:19], v[128:129], 0, v[6:7]
	global_load_dwordx4 v[132:135], v[18:19], off
	global_load_dwordx4 v[136:139], v[18:19], off offset:16
	global_load_dwordx4 v[140:143], v[18:19], off offset:32
	s_nop 0
	global_load_dwordx4 v[144:147], v[18:19], off offset:48
	v_readlane_b32 s0, v237, 47
	s_add_u32 s2, s2, s0
	v_readlane_b32 s0, v237, 46
	s_addc_u32 s3, s3, s0
	s_add_u32 s9, s9, 1
.Lfill2_p2:
	s_waitcnt vmcnt(0)
	s_cmp_le_u32 s9, 0
	s_cbranch_scc1 .Lfill2_done
	v_mov_b32_e32 v6, v24
	v_mov_b32_e32 v7, v25
	v_mov_b32_e32 v8, v26
	v_mov_b32_e32 v9, v27
	v_mov_b32_e32 v10, v28
	v_mov_b32_e32 v11, v29
	v_mov_b32_e32 v12, v30
	v_mov_b32_e32 v13, v31
	v_mov_b32_e32 v14, v32
	v_mov_b32_e32 v15, v33
	v_mov_b32_e32 v16, v34
	v_mov_b32_e32 v17, v35
	v_mov_b32_e32 v18, v36
	v_mov_b32_e32 v19, v37
	v_mov_b32_e32 v20, v38
	v_mov_b32_e32 v21, v39
	v_add_f32_e32 v5, v6, v7
	v_add_f32_e32 v6, v8, v9
	v_add_f32_e32 v7, v10, v11
	v_add_f32_e32 v8, v12, v13
	v_add_f32_e32 v5, v5, v6
	v_add_f32_e32 v9, v14, v15
	v_add_f32_e32 v10, v16, v17
	v_add_f32_e32 v6, v7, v8
	v_add_f32_e32 v5, 0, v5
	v_add_f32_e32 v11, v18, v19
	v_add_f32_e32 v12, v20, v21
	v_add_f32_e32 v7, v9, v10
	v_add_f32_e32 v5, v5, v6
	v_add_f32_e32 v8, v11, v12
	v_add_f32_e32 v5, v5, v7
	v_add_f32_e32 v5, v5, v8
	v_lshlrev_b32_e32 v6, 2, v22
	ds_bpermute_b32 v6, v6, v5
	s_mov_b64 s[4:5], exec
	v_readlane_b32 s0, v237, 50
	v_readlane_b32 s1, v237, 51
	s_and_b64 s[0:1], s[4:5], s[0:1]
	s_mov_b64 exec, s[0:1]
	s_cbranch_execz .Lfill2_j0
	s_waitcnt lgkmcnt(0)
	v_add_f32_e32 v5, v5, v6
	v_fmamk_f32 v5, v5, 0x3a000000, v2
	v_mul_f32_e32 v6, 0x4f800000, v5
	v_cmp_gt_f32_e32 vcc, s6, v5
	s_nop 1
	v_cndmask_b32_e32 v5, v5, v6, vcc
	v_sqrt_f32_e32 v6, v5
	s_nop 0
	v_add_u32_e32 v7, -1, v6
	v_fma_f32 v9, -v7, v6, v5
	v_add_u32_e32 v8, 1, v6
	v_cmp_ge_f32_e64 s[0:1], 0, v9
	s_nop 1
	v_cndmask_b32_e64 v7, v6, v7, s[0:1]
	v_fma_f32 v6, -v8, v6, v5
	v_cmp_lt_f32_e64 s[0:1], 0, v6
	s_nop 1
	v_cndmask_b32_e64 v6, v7, v8, s[0:1]
	v_mul_f32_e32 v7, 0x37800000, v6
	v_cndmask_b32_e32 v6, v6, v7, vcc
	v_cmp_class_f32_e32 vcc, v5, v3
	s_nop 1
	v_cndmask_b32_e32 v5, v6, v5, vcc
	v_div_scale_f32 v6, s[0:1], v5, v5, 1.0
	v_rcp_f32_e32 v7, v6
	s_nop 0
	v_fma_f32 v8, -v6, v7, 1.0
	v_fmac_f32_e32 v7, v8, v7
	v_div_scale_f32 v8, vcc, 1.0, v5, 1.0
	v_mul_f32_e32 v9, v8, v7
	v_fma_f32 v10, -v6, v9, v8
	v_fmac_f32_e32 v9, v10, v7
	v_fma_f32 v6, -v6, v9, v8
	v_div_fmas_f32 v6, v6, v7, v9
	v_div_fixup_f32 v5, v6, v5, 1.0
	ds_write_b32 v4, v5
.Lfill2_j0:
	s_or_b64 exec, exec, s[4:5]
	v_add_u32_e32 v4, 0x400, v4
	s_cmp_le_u32 s9, 1
	s_cbranch_scc1 .Lfill2_done
	v_mov_b32_e32 v6, v40
	v_mov_b32_e32 v7, v41
	v_mov_b32_e32 v8, v42
	v_mov_b32_e32 v9, v43
	v_mov_b32_e32 v10, v44
	v_mov_b32_e32 v11, v45
	v_mov_b32_e32 v12, v46
	v_mov_b32_e32 v13, v47
	v_mov_b32_e32 v14, v48
	v_mov_b32_e32 v15, v49
	v_mov_b32_e32 v16, v50
	v_mov_b32_e32 v17, v51
	v_mov_b32_e32 v18, v52
	v_mov_b32_e32 v19, v53
	v_mov_b32_e32 v20, v54
	v_mov_b32_e32 v21, v55
	v_add_f32_e32 v5, v6, v7
	v_add_f32_e32 v6, v8, v9
	v_add_f32_e32 v7, v10, v11
	v_add_f32_e32 v8, v12, v13
	v_add_f32_e32 v5, v5, v6
	v_add_f32_e32 v9, v14, v15
	v_add_f32_e32 v10, v16, v17
	v_add_f32_e32 v6, v7, v8
	v_add_f32_e32 v5, 0, v5
	v_add_f32_e32 v11, v18, v19
	v_add_f32_e32 v12, v20, v21
	v_add_f32_e32 v7, v9, v10
	v_add_f32_e32 v5, v5, v6
	v_add_f32_e32 v8, v11, v12
	v_add_f32_e32 v5, v5, v7
	v_add_f32_e32 v5, v5, v8
	v_lshlrev_b32_e32 v6, 2, v22
	ds_bpermute_b32 v6, v6, v5
	s_mov_b64 s[4:5], exec
	v_readlane_b32 s0, v237, 50
	v_readlane_b32 s1, v237, 51
	s_and_b64 s[0:1], s[4:5], s[0:1]
	s_mov_b64 exec, s[0:1]
	s_cbranch_execz .Lfill2_j1
	s_waitcnt lgkmcnt(0)
	v_add_f32_e32 v5, v5, v6
	v_fmamk_f32 v5, v5, 0x3a000000, v2
	v_mul_f32_e32 v6, 0x4f800000, v5
	v_cmp_gt_f32_e32 vcc, s6, v5
	s_nop 1
	v_cndmask_b32_e32 v5, v5, v6, vcc
	v_sqrt_f32_e32 v6, v5
	s_nop 0
	v_add_u32_e32 v7, -1, v6
	v_fma_f32 v9, -v7, v6, v5
	v_add_u32_e32 v8, 1, v6
	v_cmp_ge_f32_e64 s[0:1], 0, v9
	s_nop 1
	v_cndmask_b32_e64 v7, v6, v7, s[0:1]
	v_fma_f32 v6, -v8, v6, v5
	v_cmp_lt_f32_e64 s[0:1], 0, v6
	s_nop 1
	v_cndmask_b32_e64 v6, v7, v8, s[0:1]
	v_mul_f32_e32 v7, 0x37800000, v6
	v_cndmask_b32_e32 v6, v6, v7, vcc
	v_cmp_class_f32_e32 vcc, v5, v3
	s_nop 1
	v_cndmask_b32_e32 v5, v6, v5, vcc
	v_div_scale_f32 v6, s[0:1], v5, v5, 1.0
	v_rcp_f32_e32 v7, v6
	s_nop 0
	v_fma_f32 v8, -v6, v7, 1.0
	v_fmac_f32_e32 v7, v8, v7
	v_div_scale_f32 v8, vcc, 1.0, v5, 1.0
	v_mul_f32_e32 v9, v8, v7
	v_fma_f32 v10, -v6, v9, v8
	v_fmac_f32_e32 v9, v10, v7
	v_fma_f32 v6, -v6, v9, v8
	v_div_fmas_f32 v6, v6, v7, v9
	v_div_fixup_f32 v5, v6, v5, 1.0
	ds_write_b32 v4, v5
; template <class Sched> __device__ __forceinline__ void fill_rstd_table(PG8_LAS float* tab, const float* ssq, const Sched& S) {
;     ...
;     for (int i = 0; S.next(i, u); ++i) { const f32x4* p = (const f32x4*)(ssq + (size_t)(u.pm * BM + r) * 32 + hf * 16); float s = 0.f;
; #pragma unroll
;         for (int j = 0; j < 4; ++j) { const f32x4 a = p[j]; s += (a[0] + a[1]) + (a[2] + a[3]); }
;         s += __shfl_xor(s, 1);
;         if (hf == 0) tab[i * 256 + r] = 1.0f / sqrtf(s * (1.0f / 2048.0f) + RMS_EPS); }
.Lfill2_j1:
	s_or_b64 exec, exec, s[4:5]
	v_add_u32_e32 v4, 0x400, v4
	s_cmp_le_u32 s9, 2
	s_cbranch_scc1 .Lfill2_done
	v_mov_b32_e32 v6, v56
	v_mov_b32_e32 v7, v57
	v_mov_b32_e32 v8, v58
	v_mov_b32_e32 v9, v59
	v_mov_b32_e32 v10, v60
	v_mov_b32_e32 v11, v61
	v_mov_b32_e32 v12, v62
	v_mov_b32_e32 v13, v63
	v_mov_b32_e32 v14, v64
	v_mov_b32_e32 v15, v65
	v_mov_b32_e32 v16, v66
	v_mov_b32_e32 v17, v67
	v_mov_b32_e32 v18, v68
	v_mov_b32_e32 v19, v69
	v_mov_b32_e32 v20, v70
	v_mov_b32_e32 v21, v71
	v_add_f32_e32 v5, v6, v7
	v_add_f32_e32 v6, v8, v9
	v_add_f32_e32 v7, v10, v11
	v_add_f32_e32 v8, v12, v13
	v_add_f32_e32 v5, v5, v6
	v_add_f32_e32 v9, v14, v15
	v_add_f32_e32 v10, v16, v17
	v_add_f32_e32 v6, v7, v8
	v_add_f32_e32 v5, 0, v5
	v_add_f32_e32 v11, v18, v19
	v_add_f32_e32 v12, v20, v21
	v_add_f32_e32 v7, v9, v10
	v_add_f32_e32 v5, v5, v6
	v_add_f32_e32 v8, v11, v12
	v_add_f32_e32 v5, v5, v7
	v_add_f32_e32 v5, v5, v8
	v_lshlrev_b32_e32 v6, 2, v22
	ds_bpermute_b32 v6, v6, v5
	s_mov_b64 s[4:5], exec
	v_readlane_b32 s0, v237, 50
	v_readlane_b32 s1, v237, 51
	s_and_b64 s[0:1], s[4:5], s[0:1]
	s_mov_b64 exec, s[0:1]
	s_cbranch_execz .Lfill2_j2
	s_waitcnt lgkmcnt(0)
	v_add_f32_e32 v5, v5, v6
	v_fmamk_f32 v5, v5, 0x3a000000, v2
	v_mul_f32_e32 v6, 0x4f800000, v5
	v_cmp_gt_f32_e32 vcc, s6, v5
	s_nop 1
	v_cndmask_b32_e32 v5, v5, v6, vcc
	v_sqrt_f32_e32 v6, v5
	s_nop 0
	v_add_u32_e32 v7, -1, v6
	v_fma_f32 v9, -v7, v6, v5
	v_add_u32_e32 v8, 1, v6
	v_cmp_ge_f32_e64 s[0:1], 0, v9
	s_nop 1
	v_cndmask_b32_e64 v7, v6, v7, s[0:1]
	v_fma_f32 v6, -v8, v6, v5
	v_cmp_lt_f32_e64 s[0:1], 0, v6
	s_nop 1
	v_cndmask_b32_e64 v6, v7, v8, s[0:1]
	v_mul_f32_e32 v7, 0x37800000, v6
	v_cndmask_b32_e32 v6, v6, v7, vcc
	v_cmp_class_f32_e32 vcc, v5, v3
	s_nop 1
	v_cndmask_b32_e32 v5, v6, v5, vcc
	v_div_scale_f32 v6, s[0:1], v5, v5, 1.0
	v_rcp_f32_e32 v7, v6
	s_nop 0
	v_fma_f32 v8, -v6, v7, 1.0
	v_fmac_f32_e32 v7, v8, v7
	v_div_scale_f32 v8, vcc, 1.0, v5, 1.0
	v_mul_f32_e32 v9, v8, v7
	v_fma_f32 v10, -v6, v9, v8
	v_fmac_f32_e32 v9, v10, v7
	v_fma_f32 v6, -v6, v9, v8
	v_div_fmas_f32 v6, v6, v7, v9
	v_div_fixup_f32 v5, v6, v5, 1.0
	ds_write_b32 v4, v5
.Lfill2_j2:
	s_or_b64 exec, exec, s[4:5]
	v_add_u32_e32 v4, 0x400, v4
	s_cmp_le_u32 s9, 3
	s_cbranch_scc1 .Lfill2_done
	v_mov_b32_e32 v6, v132
	v_mov_b32_e32 v7, v133
	v_mov_b32_e32 v8, v134
	v_mov_b32_e32 v9, v135
	v_mov_b32_e32 v10, v136
	v_mov_b32_e32 v11, v137
	v_mov_b32_e32 v12, v138
	v_mov_b32_e32 v13, v139
	v_mov_b32_e32 v14, v140
	v_mov_b32_e32 v15, v141
	v_mov_b32_e32 v16, v142
	v_mov_b32_e32 v17, v143
	v_mov_b32_e32 v18, v144
	v_mov_b32_e32 v19, v145
	v_mov_b32_e32 v20, v146
	v_mov_b32_e32 v21, v147
	v_add_f32_e32 v5, v6, v7
	v_add_f32_e32 v6, v8, v9
	v_add_f32_e32 v7, v10, v11
	v_add_f32_e32 v8, v12, v13
	v_add_f32_e32 v5, v5, v6
	v_add_f32_e32 v9, v14, v15
	v_add_f32_e32 v10, v16, v17
	v_add_f32_e32 v6, v7, v8
	v_add_f32_e32 v5, 0, v5
	v_add_f32_e32 v11, v18, v19
	v_add_f32_e32 v12, v20, v21
	v_add_f32_e32 v7, v9, v10
	v_add_f32_e32 v5, v5, v6
	v_add_f32_e32 v8, v11, v12
	v_add_f32_e32 v5, v5, v7
	v_add_f32_e32 v5, v5, v8
	v_lshlrev_b32_e32 v6, 2, v22
	ds_bpermute_b32 v6, v6, v5
	s_mov_b64 s[4:5], exec
	v_readlane_b32 s0, v237, 50
	v_readlane_b32 s1, v237, 51
	s_and_b64 s[0:1], s[4:5], s[0:1]
	s_mov_b64 exec, s[0:1]
	s_cbranch_execz .Lfill2_j3
	s_waitcnt lgkmcnt(0)
	v_add_f32_e32 v5, v5, v6
	v_fmamk_f32 v5, v5, 0x3a000000, v2
	v_mul_f32_e32 v6, 0x4f800000, v5
	v_cmp_gt_f32_e32 vcc, s6, v5
	s_nop 1
	v_cndmask_b32_e32 v5, v5, v6, vcc
	v_sqrt_f32_e32 v6, v5
	s_nop 0
	v_add_u32_e32 v7, -1, v6
	v_fma_f32 v9, -v7, v6, v5
	v_add_u32_e32 v8, 1, v6
	v_cmp_ge_f32_e64 s[0:1], 0, v9
	s_nop 1
	v_cndmask_b32_e64 v7, v6, v7, s[0:1]
	v_fma_f32 v6, -v8, v6, v5
	v_cmp_lt_f32_e64 s[0:1], 0, v6
	s_nop 1
	v_cndmask_b32_e64 v6, v7, v8, s[0:1]
	v_mul_f32_e32 v7, 0x37800000, v6
	v_cndmask_b32_e32 v6, v6, v7, vcc
	v_cmp_class_f32_e32 vcc, v5, v3
	s_nop 1
	v_cndmask_b32_e32 v5, v6, v5, vcc
	v_div_scale_f32 v6, s[0:1], v5, v5, 1.0
	v_rcp_f32_e32 v7, v6
	s_nop 0
	v_fma_f32 v8, -v6, v7, 1.0
	v_fmac_f32_e32 v7, v8, v7
	v_div_scale_f32 v8, vcc, 1.0, v5, 1.0
	v_mul_f32_e32 v9, v8, v7
	v_fma_f32 v10, -v6, v9, v8
	v_fmac_f32_e32 v9, v10, v7
	v_fma_f32 v6, -v6, v9, v8
	v_div_fmas_f32 v6, v6, v7, v9
	v_div_fixup_f32 v5, v6, v5, 1.0
	ds_write_b32 v4, v5

;     __host__ __device__ bool next(int i, Unit& u) const {
;         const long L = (long)i * G + c; if (L >= nwg) return false;
;         int wgid = (int)L; { const int q = nwg / NXCD, r = nwg % NXCD, xcd = wgid % NXCD, off = wgid / NXCD; wgid = (xcd < r ? xcd * (q + 1) : r * (q + 1) + (xcd - r) * q) + off; }
;         const int nig = WGM * nN, gid = wgid / nig, fm = gid * WGM, gsz = (nM - fm) < WGM ? (nM - fm) : WGM;
;         u.pm = fm + ((wgid % nig) % gsz); u.pn = (wgid % nig) / gsz; return true;
; template <class Sched> __device__ __forceinline__ void fill_rstd_table(PG8_LAS float* tab, const float* ssq, const Sched& S) {
;     ...
;     for (int i = 0; S.next(i, u); ++i) { const f32x4* p = (const f32x4*)(ssq + (size_t)(u.pm * BM + r) * 32 + hf * 16); float s = 0.f;
; #pragma unroll
;         for (int j = 0; j < 4; ++j) { const f32x4 a = p[j]; s += (a[0] + a[1]) + (a[2] + a[3]); }
.LBB0_1696:
	s_andn2_b64 vcc, exec, s[0:1]
	s_cbranch_vccnz .LBB0_1884
	v_mov_b64_e32 v[0:1], 0x57f
	s_movk_i32 s6, 0xb1
	v_mov_b32_e32 v2, 0x358637bd
	s_mov_b32 s7, 0xf800000
	v_mov_b32_e32 v3, 0x260
	s_mov_b64 s[2:3], s[50:51]
	s_waitcnt vmcnt(0)
	s_mov_b32 s10, 0
	v_cmp_gt_i64_e32 vcc, s[2:3], v[0:1]
	s_cbranch_vccnz .Lfill3_p2
	s_ashr_i32 s0, s2, 31
	s_lshr_b32 s0, s0, 29
	s_add_i32 s0, s2, s0
	s_ashr_i32 s1, s0, 3
	s_and_b32 s0, s0, -8
	s_sub_i32 s0, s2, s0
	s_cmp_lt_i32 s0, 0
	s_cselect_b32 s4, s6, 0xb0
	s_mul_i32 s0, s0, s4
	s_add_i32 s0, s0, s1
	s_mul_hi_i32 s1, s0, 0x2e8ba2e9
	s_lshr_b32 s4, s1, 31
	s_ashr_i32 s1, s1, 6
	s_add_i32 s1, s1, s4
	s_lshl_b32 s4, s1, 3
	s_sub_i32 s5, 32, s4
	s_min_i32 s5, s5, 8
	s_abs_i32 s5, s5
	v_cvt_f32_u32_e32 v4, s5
	s_sub_i32 s8, 0, s5
	s_mulk_i32 s1, 0x160
	s_sub_i32 s0, s0, s1
	v_rcp_iflag_f32_e32 v4, v4
	s_ashr_i32 s1, s0, 31
	s_abs_i32 s0, s0
	v_cmp_lt_i32_e32 vcc, v176, v177
	v_mul_f32_e32 v4, 0x4f7ffffe, v4
	v_cvt_u32_f32_e32 v4, v4
	v_cndmask_b32_e32 v20, v175, v176, vcc
	v_readfirstlane_b32 s9, v4
	s_mul_i32 s8, s8, s9
	s_mul_hi_u32 s8, s9, s8
	s_add_i32 s9, s9, s8
	s_mul_hi_u32 s8, s0, s9
	s_mul_i32 s8, s8, s5
	s_sub_i32 s0, s0, s8
	s_sub_i32 s8, s0, s5
	s_cmp_ge_u32 s0, s5
	s_cselect_b32 s0, s8, s0
	s_sub_i32 s8, s0, s5
	s_cmp_ge_u32 s0, s5
	s_cselect_b32 s0, s8, s0
	s_xor_b32 s0, s0, s1
	s_sub_i32 s0, s0, s1
	s_add_i32 s4, s4, s0
	v_lshl_add_u32 v4, s4, 8, v173
	s_waitcnt lgkmcnt(0)
	v_ashrrev_i32_e32 v5, 31, v4
	v_lshlrev_b64 v[4:5], 7, v[4:5]
	v_lshl_add_u64 v[16:17], v[128:129], 0, v[4:5]
	global_load_dwordx4 v[24:27], v[16:17], off
	global_load_dwordx4 v[28:31], v[16:17], off offset:16
	global_load_dwordx4 v[32:35], v[16:17], off offset:32
	s_nop 0
	global_load_dwordx4 v[36:39], v[16:17], off offset:48
	v_readlane_b32 s0, v236, 0
	s_add_u32 s2, s2, s0
	v_readlane_b32 s0, v236, 1
	s_addc_u32 s3, s3, s0
	s_add_u32 s10, s10, 1
	v_cmp_gt_i64_e32 vcc, s[2:3], v[0:1]
	s_cbranch_vccnz .Lfill3_p2
	s_ashr_i32 s0, s2, 31
	s_lshr_b32 s0, s0, 29
	s_add_i32 s0, s2, s0
	s_ashr_i32 s1, s0, 3
	s_and_b32 s0, s0, -8
	s_sub_i32 s0, s2, s0
	s_cmp_lt_i32 s0, 0
	s_cselect_b32 s4, s6, 0xb0
	s_mul_i32 s0, s0, s4
	s_add_i32 s0, s0, s1
	s_mul_hi_i32 s1, s0, 0x2e8ba2e9
	s_lshr_b32 s4, s1, 31
	s_ashr_i32 s1, s1, 6
	s_add_i32 s1, s1, s4
	s_lshl_b32 s4, s1, 3
	s_sub_i32 s5, 32, s4
	s_min_i32 s5, s5, 8
	s_abs_i32 s5, s5
	v_cvt_f32_u32_e32 v4, s5
	s_sub_i32 s8, 0, s5
	s_mulk_i32 s1, 0x160
	s_sub_i32 s0, s0, s1
	v_rcp_iflag_f32_e32 v4, v4
	s_ashr_i32 s1, s0, 31
	s_abs_i32 s0, s0
	v_cmp_lt_i32_e32 vcc, v176, v177
	v_mul_f32_e32 v4, 0x4f7ffffe, v4
	v_cvt_u32_f32_e32 v4, v4
	v_cndmask_b32_e32 v20, v175, v176, vcc
	v_readfirstlane_b32 s9, v4
	s_mul_i32 s8, s8, s9
	s_mul_hi_u32 s8, s9, s8
	s_add_i32 s9, s9, s8
	s_mul_hi_u32 s8, s0, s9
	s_mul_i32 s8, s8, s5
	s_sub_i32 s0, s0, s8
	s_sub_i32 s8, s0, s5
	s_cmp_ge_u32 s0, s5
	s_cselect_b32 s0, s8, s0
	s_sub_i32 s8, s0, s5
	s_cmp_ge_u32 s0, s5
	s_cselect_b32 s0, s8, s0
	s_xor_b32 s0, s0, s1
	s_sub_i32 s0, s0, s1
	s_add_i32 s4, s4, s0
	v_lshl_add_u32 v4, s4, 8, v173
	s_waitcnt lgkmcnt(0)
	v_ashrrev_i32_e32 v5, 31, v4
	v_lshlrev_b64 v[4:5], 7, v[4:5]
	v_lshl_add_u64 v[16:17], v[128:129], 0, v[4:5]
	global_load_dwordx4 v[40:43], v[16:17], off
	global_load_dwordx4 v[44:47], v[16:17], off offset:16
	global_load_dwordx4 v[48:51], v[16:17], off offset:32
	s_nop 0
	global_load_dwordx4 v[52:55], v[16:17], off offset:48
	v_readlane_b32 s0, v236, 0
	s_add_u32 s2, s2, s0
	v_readlane_b32 s0, v236, 1
	s_addc_u32 s3, s3, s0
	s_add_u32 s10, s10, 1
	v_cmp_gt_i64_e32 vcc, s[2:3], v[0:1]
	s_cbranch_vccnz .Lfill3_p2
	s_ashr_i32 s0, s2, 31
	s_lshr_b32 s0, s0, 29
	s_add_i32 s0, s2, s0
	s_ashr_i32 s1, s0, 3
	s_and_b32 s0, s0, -8
	s_sub_i32 s0, s2, s0
	s_cmp_lt_i32 s0, 0
	s_cselect_b32 s4, s6, 0xb0
	s_mul_i32 s0, s0, s4
	s_add_i32 s0, s0, s1
	s_mul_hi_i32 s1, s0, 0x2e8ba2e9
	s_lshr_b32 s4, s1, 31
	s_ashr_i32 s1, s1, 6
	s_add_i32 s1, s1, s4
	s_lshl_b32 s4, s1, 3
	s_sub_i32 s5, 32, s4
	s_min_i32 s5, s5, 8
	s_abs_i32 s5, s5
	v_cvt_f32_u32_e32 v4, s5
	s_sub_i32 s8, 0, s5
	s_mulk_i32 s1, 0x160
	s_sub_i32 s0, s0, s1
	v_rcp_iflag_f32_e32 v4, v4
	s_ashr_i32 s1, s0, 31
	s_abs_i32 s0, s0
	v_cmp_lt_i32_e32 vcc, v176, v177
	v_mul_f32_e32 v4, 0x4f7ffffe, v4
	v_cvt_u32_f32_e32 v4, v4
	v_cndmask_b32_e32 v20, v175, v176, vcc
	v_readfirstlane_b32 s9, v4
	s_mul_i32 s8, s8, s9
	s_mul_hi_u32 s8, s9, s8
	s_add_i32 s9, s9, s8
	s_mul_hi_u32 s8, s0, s9
	s_mul_i32 s8, s8, s5
	s_sub_i32 s0, s0, s8
	s_sub_i32 s8, s0, s5
	s_cmp_ge_u32 s0, s5
	s_cselect_b32 s0, s8, s0
	s_sub_i32 s8, s0, s5
	s_cmp_ge_u32 s0, s5
	s_cselect_b32 s0, s8, s0
	s_xor_b32 s0, s0, s1
	s_sub_i32 s0, s0, s1
	s_add_i32 s4, s4, s0
	v_lshl_add_u32 v4, s4, 8, v173
	s_waitcnt lgkmcnt(0)
	v_ashrrev_i32_e32 v5, 31, v4
	v_lshlrev_b64 v[4:5], 7, v[4:5]
	v_lshl_add_u64 v[16:17], v[128:129], 0, v[4:5]
	global_load_dwordx4 v[56:59], v[16:17], off
	global_load_dwordx4 v[60:63], v[16:17], off offset:16
	global_load_dwordx4 v[64:67], v[16:17], off offset:32
	s_nop 0
	global_load_dwordx4 v[68:71], v[16:17], off offset:48
	v_readlane_b32 s0, v236, 0
	s_add_u32 s2, s2, s0
	v_readlane_b32 s0, v236, 1
	s_addc_u32 s3, s3, s0
	s_add_u32 s10, s10, 1
	v_cmp_gt_i64_e32 vcc, s[2:3], v[0:1]
	s_cbranch_vccnz .Lfill3_p2
;     __host__ __device__ bool next(int i, Unit& u) const {
;         const long L = (long)i * G + c; if (L >= nwg) return false;
;         int wgid = (int)L; { const int q = nwg / NXCD, r = nwg % NXCD, xcd = wgid % NXCD, off = wgid / NXCD; wgid = (xcd < r ? xcd * (q + 1) : r * (q + 1) + (xcd - r) * q) + off; }
;         const int nig = WGM * nN, gid = wgid / nig, fm = gid * WGM, gsz = (nM - fm) < WGM ? (nM - fm) : WGM;
;         u.pm = fm + ((wgid % nig) % gsz); u.pn = (wgid % nig) / gsz; return true;
; template <class Sched> __device__ __forceinline__ void fill_rstd_table(PG8_LAS float* tab, const float* ssq, const Sched& S) {
;     ...
;     for (int i = 0; S.next(i, u); ++i) { const f32x4* p = (const f32x4*)(ssq + (size_t)(u.pm * BM + r) * 32 + hf * 16); float s = 0.f;
; #pragma unroll
;         for (int j = 0; j < 4; ++j) { const f32x4 a = p[j]; s += (a[0] + a[1]) + (a[2] + a[3]); }
	s_ashr_i32 s0, s2, 31
	s_lshr_b32 s0, s0, 29
	s_add_i32 s0, s2, s0
	s_ashr_i32 s1, s0, 3
	s_and_b32 s0, s0, -8
	s_sub_i32 s0, s2, s0
	s_cmp_lt_i32 s0, 0
	s_cselect_b32 s4, s6, 0xb0
	s_mul_i32 s0, s0, s4
	s_add_i32 s0, s0, s1
	s_mul_hi_i32 s1, s0, 0x2e8ba2e9
	s_lshr_b32 s4, s1, 31
	s_ashr_i32 s1, s1, 6
	s_add_i32 s1, s1, s4
	s_lshl_b32 s4, s1, 3
	s_sub_i32 s5, 32, s4
	s_min_i32 s5, s5, 8
	s_abs_i32 s5, s5
	v_cvt_f32_u32_e32 v4, s5
	s_sub_i32 s8, 0, s5
	s_mulk_i32 s1, 0x160
	s_sub_i32 s0, s0, s1
	v_rcp_iflag_f32_e32 v4, v4
	s_ashr_i32 s1, s0, 31
	s_abs_i32 s0, s0
	v_cmp_lt_i32_e32 vcc, v176, v177
	v_mul_f32_e32 v4, 0x4f7ffffe, v4
	v_cvt_u32_f32_e32 v4, v4
	v_cndmask_b32_e32 v20, v175, v176, vcc
	v_readfirstlane_b32 s9, v4
	s_mul_i32 s8, s8, s9
	s_mul_hi_u32 s8, s9, s8
	s_add_i32 s9, s9, s8
	s_mul_hi_u32 s8, s0, s9
	s_mul_i32 s8, s8, s5
	s_sub_i32 s0, s0, s8
	s_sub_i32 s8, s0, s5
	s_cmp_ge_u32 s0, s5
	s_cselect_b32 s0, s8, s0
	s_sub_i32 s8, s0, s5
	s_cmp_ge_u32 s0, s5
	s_cselect_b32 s0, s8, s0
	s_xor_b32 s0, s0, s1
	s_sub_i32 s0, s0, s1
	s_add_i32 s4, s4, s0
	v_lshl_add_u32 v4, s4, 8, v173
	s_waitcnt lgkmcnt(0)
	v_ashrrev_i32_e32 v5, 31, v4
	v_lshlrev_b64 v[4:5], 7, v[4:5]
	v_lshl_add_u64 v[16:17], v[128:129], 0, v[4:5]
	global_load_dwordx4 v[132:135], v[16:17], off
	global_load_dwordx4 v[136:139], v[16:17], off offset:16
	global_load_dwordx4 v[140:143], v[16:17], off offset:32
	s_nop 0
	global_load_dwordx4 v[144:147], v[16:17], off offset:48
	v_readlane_b32 s0, v236, 0
	s_add_u32 s2, s2, s0
	v_readlane_b32 s0, v236, 1
	s_addc_u32 s3, s3, s0
	s_add_u32 s10, s10, 1
	v_cmp_gt_i64_e32 vcc, s[2:3], v[0:1]
	s_cbranch_vccnz .Lfill3_p2
	s_ashr_i32 s0, s2, 31
	s_lshr_b32 s0, s0, 29
	s_add_i32 s0, s2, s0
	s_ashr_i32 s1, s0, 3
	s_and_b32 s0, s0, -8
	s_sub_i32 s0, s2, s0
	s_cmp_lt_i32 s0, 0
	s_cselect_b32 s4, s6, 0xb0
	s_mul_i32 s0, s0, s4
	s_add_i32 s0, s0, s1
	s_mul_hi_i32 s1, s0, 0x2e8ba2e9
	s_lshr_b32 s4, s1, 31
	s_ashr_i32 s1, s1, 6
	s_add_i32 s1, s1, s4
	s_lshl_b32 s4, s1, 3
	s_sub_i32 s5, 32, s4
	s_min_i32 s5, s5, 8
	s_abs_i32 s5, s5
	v_cvt_f32_u32_e32 v4, s5
	s_sub_i32 s8, 0, s5
	s_mulk_i32 s1, 0x160
	s_sub_i32 s0, s0, s1
	v_rcp_iflag_f32_e32 v4, v4
	s_ashr_i32 s1, s0, 31
	s_abs_i32 s0, s0
	v_cmp_lt_i32_e32 vcc, v176, v177
	v_mul_f32_e32 v4, 0x4f7ffffe, v4
	v_cvt_u32_f32_e32 v4, v4
	v_cndmask_b32_e32 v20, v175, v176, vcc
	v_readfirstlane_b32 s9, v4
	s_mul_i32 s8, s8, s9
	s_mul_hi_u32 s8, s9, s8
	s_add_i32 s9, s9, s8
	s_mul_hi_u32 s8, s0, s9
	s_mul_i32 s8, s8, s5
	s_sub_i32 s0, s0, s8
	s_sub_i32 s8, s0, s5
	s_cmp_ge_u32 s0, s5
	s_cselect_b32 s0, s8, s0
	s_sub_i32 s8, s0, s5
	s_cmp_ge_u32 s0, s5
	s_cselect_b32 s0, s8, s0
	s_xor_b32 s0, s0, s1
	s_sub_i32 s0, s0, s1
	s_add_i32 s4, s4, s0
	v_lshl_add_u32 v4, s4, 8, v173
	s_waitcnt lgkmcnt(0)
	v_ashrrev_i32_e32 v5, 31, v4
	v_lshlrev_b64 v[4:5], 7, v[4:5]
	v_lshl_add_u64 v[16:17], v[128:129], 0, v[4:5]
	global_load_dwordx4 v[148:151], v[16:17], off
	global_load_dwordx4 v[152:155], v[16:17], off offset:16
	global_load_dwordx4 v[156:159], v[16:17], off offset:32
	s_nop 0
	global_load_dwordx4 v[160:163], v[16:17], off offset:48
	v_readlane_b32 s0, v236, 0
	s_add_u32 s2, s2, s0
	v_readlane_b32 s0, v236, 1
	s_addc_u32 s3, s3, s0
	s_add_u32 s10, s10, 1
	v_cmp_gt_i64_e32 vcc, s[2:3], v[0:1]
	s_cbranch_vccnz .Lfill3_p2
	s_ashr_i32 s0, s2, 31
	s_lshr_b32 s0, s0, 29
	s_add_i32 s0, s2, s0
	s_ashr_i32 s1, s0, 3
	s_and_b32 s0, s0, -8
	s_sub_i32 s0, s2, s0
	s_cmp_lt_i32 s0, 0
	s_cselect_b32 s4, s6, 0xb0
	s_mul_i32 s0, s0, s4
	s_add_i32 s0, s0, s1
	s_mul_hi_i32 s1, s0, 0x2e8ba2e9
	s_lshr_b32 s4, s1, 31
	s_ashr_i32 s1, s1, 6
	s_add_i32 s1, s1, s4
	s_lshl_b32 s4, s1, 3
	s_sub_i32 s5, 32, s4
	s_min_i32 s5, s5, 8
	s_abs_i32 s5, s5
	v_cvt_f32_u32_e32 v4, s5
	s_sub_i32 s8, 0, s5
	s_mulk_i32 s1, 0x160
	s_sub_i32 s0, s0, s1
	v_rcp_iflag_f32_e32 v4, v4
	s_ashr_i32 s1, s0, 31
	s_abs_i32 s0, s0
	v_cmp_lt_i32_e32 vcc, v176, v177
	v_mul_f32_e32 v4, 0x4f7ffffe, v4
	v_cvt_u32_f32_e32 v4, v4
	v_cndmask_b32_e32 v20, v175, v176, vcc
	v_readfirstlane_b32 s9, v4
	s_mul_i32 s8, s8, s9
	s_mul_hi_u32 s8, s9, s8
	s_add_i32 s9, s9, s8
	s_mul_hi_u32 s8, s0, s9
	s_mul_i32 s8, s8, s5
	s_sub_i32 s0, s0, s8
	s_sub_i32 s8, s0, s5
	s_cmp_ge_u32 s0, s5
	s_cselect_b32 s0, s8, s0
	s_sub_i32 s8, s0, s5
	s_cmp_ge_u32 s0, s5
	s_cselect_b32 s0, s8, s0
	s_xor_b32 s0, s0, s1
	s_sub_i32 s0, s0, s1
	s_add_i32 s4, s4, s0
	v_lshl_add_u32 v4, s4, 8, v173
	s_waitcnt lgkmcnt(0)
	v_ashrrev_i32_e32 v5, 31, v4
	v_lshlrev_b64 v[4:5], 7, v[4:5]
	v_lshl_add_u64 v[16:17], v[128:129], 0, v[4:5]
	global_load_dwordx4 v[180:183], v[16:17], off
	global_load_dwordx4 v[184:187], v[16:17], off offset:16
	global_load_dwordx4 v[188:191], v[16:17], off offset:32
	s_nop 0
	global_load_dwordx4 v[192:195], v[16:17], off offset:48
	v_readlane_b32 s0, v236, 0
	s_add_u32 s2, s2, s0
	v_readlane_b32 s0, v236, 1
	s_addc_u32 s3, s3, s0
	s_add_u32 s10, s10, 1
; template <class Sched> __device__ __forceinline__ void fill_rstd_table(PG8_LAS float* tab, const float* ssq, const Sched& S) {
;     ...
;     for (int i = 0; S.next(i, u); ++i) { const f32x4* p = (const f32x4*)(ssq + (size_t)(u.pm * BM + r) * 32 + hf * 16); float s = 0.f;
; #pragma unroll
;         for (int j = 0; j < 4; ++j) { const f32x4 a = p[j]; s += (a[0] + a[1]) + (a[2] + a[3]); }
;         s += __shfl_xor(s, 1);
;         if (hf == 0) tab[i * 256 + r] = 1.0f / sqrtf(s * (1.0f / 2048.0f) + RMS_EPS); }
.Lfill3_p2:
	s_waitcnt vmcnt(0)
	s_cmp_le_u32 s10, 0
	s_cbranch_scc1 .Lfill3_done
	v_mov_b32_e32 v4, v24
	v_mov_b32_e32 v5, v25
	v_mov_b32_e32 v6, v26
	v_mov_b32_e32 v7, v27
	v_mov_b32_e32 v8, v28
	v_mov_b32_e32 v9, v29
	v_mov_b32_e32 v10, v30
	v_mov_b32_e32 v11, v31
	v_mov_b32_e32 v12, v32
	v_mov_b32_e32 v13, v33
	v_mov_b32_e32 v14, v34
	v_mov_b32_e32 v15, v35
	v_mov_b32_e32 v16, v36
	v_mov_b32_e32 v17, v37
	v_mov_b32_e32 v18, v38
	v_mov_b32_e32 v19, v39
	v_add_f32_e32 v4, v4, v5
	v_add_f32_e32 v5, v6, v7
	v_add_f32_e32 v6, v8, v9
	v_add_f32_e32 v7, v10, v11
	v_add_f32_e32 v4, v4, v5
	v_add_f32_e32 v8, v12, v13
	v_add_f32_e32 v9, v14, v15
	v_add_f32_e32 v5, v6, v7
	v_add_f32_e32 v4, 0, v4
	v_add_f32_e32 v10, v16, v17
	v_add_f32_e32 v11, v18, v19
	v_add_f32_e32 v6, v8, v9
	v_add_f32_e32 v4, v4, v5
	v_add_f32_e32 v7, v10, v11
	v_add_f32_e32 v4, v4, v6
	v_add_f32_e32 v4, v4, v7
	v_lshlrev_b32_e32 v5, 2, v20
	ds_bpermute_b32 v5, v5, v4
	s_mov_b64 s[4:5], exec
	v_readlane_b32 s0, v237, 50
	v_readlane_b32 s1, v237, 51
	s_and_b64 s[0:1], s[4:5], s[0:1]
	s_mov_b64 exec, s[0:1]
	s_cbranch_execz .Lfill3_j0
	s_waitcnt lgkmcnt(0)
	v_add_f32_e32 v4, v4, v5
	v_fmamk_f32 v4, v4, 0x3a000000, v2
	v_mul_f32_e32 v5, 0x4f800000, v4
	v_cmp_gt_f32_e32 vcc, s7, v4
	s_nop 1
	v_cndmask_b32_e32 v4, v4, v5, vcc
	v_sqrt_f32_e32 v5, v4
	s_nop 0
	v_add_u32_e32 v6, -1, v5
	v_fma_f32 v8, -v6, v5, v4
	v_add_u32_e32 v7, 1, v5
	v_cmp_ge_f32_e64 s[0:1], 0, v8
	s_nop 1
	v_cndmask_b32_e64 v6, v5, v6, s[0:1]
	v_fma_f32 v5, -v7, v5, v4
	v_cmp_lt_f32_e64 s[0:1], 0, v5
	s_nop 1
	v_cndmask_b32_e64 v5, v6, v7, s[0:1]
	v_mul_f32_e32 v6, 0x37800000, v5
	v_cndmask_b32_e32 v5, v5, v6, vcc
	v_cmp_class_f32_e32 vcc, v4, v3
	s_nop 1
	v_cndmask_b32_e32 v4, v5, v4, vcc
	v_div_scale_f32 v5, s[0:1], v4, v4, 1.0
	v_rcp_f32_e32 v6, v5
	s_nop 0
	v_fma_f32 v7, -v5, v6, 1.0
	v_fmac_f32_e32 v6, v7, v6
	v_div_scale_f32 v7, vcc, 1.0, v4, 1.0
	v_mul_f32_e32 v8, v7, v6
	v_fma_f32 v9, -v5, v8, v7
	v_fmac_f32_e32 v8, v9, v6
	v_fma_f32 v5, -v5, v8, v7
	v_div_fmas_f32 v5, v5, v6, v8
	v_div_fixup_f32 v4, v5, v4, 1.0
	ds_write_b32 v174, v4
.Lfill3_j0:
	s_or_b64 exec, exec, s[4:5]
	v_add_u32_e32 v174, 0x400, v174
	s_cmp_le_u32 s10, 1
	s_cbranch_scc1 .Lfill3_done
	v_mov_b32_e32 v4, v40
	v_mov_b32_e32 v5, v41
	v_mov_b32_e32 v6, v42
	v_mov_b32_e32 v7, v43
	v_mov_b32_e32 v8, v44
	v_mov_b32_e32 v9, v45
	v_mov_b32_e32 v10, v46
	v_mov_b32_e32 v11, v47
	v_mov_b32_e32 v12, v48
	v_mov_b32_e32 v13, v49
	v_mov_b32_e32 v14, v50
	v_mov_b32_e32 v15, v51
	v_mov_b32_e32 v16, v52
	v_mov_b32_e32 v17, v53
	v_mov_b32_e32 v18, v54
	v_mov_b32_e32 v19, v55
	v_add_f32_e32 v4, v4, v5
	v_add_f32_e32 v5, v6, v7
	v_add_f32_e32 v6, v8, v9
	v_add_f32_e32 v7, v10, v11
	v_add_f32_e32 v4, v4, v5
	v_add_f32_e32 v8, v12, v13
	v_add_f32_e32 v9, v14, v15
	v_add_f32_e32 v5, v6, v7
	v_add_f32_e32 v4, 0, v4
	v_add_f32_e32 v10, v16, v17
	v_add_f32_e32 v11, v18, v19
	v_add_f32_e32 v6, v8, v9
	v_add_f32_e32 v4, v4, v5
	v_add_f32_e32 v7, v10, v11
	v_add_f32_e32 v4, v4, v6
	v_add_f32_e32 v4, v4, v7
	v_lshlrev_b32_e32 v5, 2, v20
	ds_bpermute_b32 v5, v5, v4
	s_mov_b64 s[4:5], exec
	v_readlane_b32 s0, v237, 50
	v_readlane_b32 s1, v237, 51
	s_and_b64 s[0:1], s[4:5], s[0:1]
	s_mov_b64 exec, s[0:1]
	s_cbranch_execz .Lfill3_j1
	s_waitcnt lgkmcnt(0)
	v_add_f32_e32 v4, v4, v5
	v_fmamk_f32 v4, v4, 0x3a000000, v2
	v_mul_f32_e32 v5, 0x4f800000, v4
	v_cmp_gt_f32_e32 vcc, s7, v4
	s_nop 1
	v_cndmask_b32_e32 v4, v4, v5, vcc
	v_sqrt_f32_e32 v5, v4
	s_nop 0
	v_add_u32_e32 v6, -1, v5
	v_fma_f32 v8, -v6, v5, v4
	v_add_u32_e32 v7, 1, v5
	v_cmp_ge_f32_e64 s[0:1], 0, v8
	s_nop 1
	v_cndmask_b32_e64 v6, v5, v6, s[0:1]
	v_fma_f32 v5, -v7, v5, v4
	v_cmp_lt_f32_e64 s[0:1], 0, v5
	s_nop 1
	v_cndmask_b32_e64 v5, v6, v7, s[0:1]
	v_mul_f32_e32 v6, 0x37800000, v5
	v_cndmask_b32_e32 v5, v5, v6, vcc
	v_cmp_class_f32_e32 vcc, v4, v3
	s_nop 1
	v_cndmask_b32_e32 v4, v5, v4, vcc
	v_div_scale_f32 v5, s[0:1], v4, v4, 1.0
	v_rcp_f32_e32 v6, v5
	s_nop 0
	v_fma_f32 v7, -v5, v6, 1.0
	v_fmac_f32_e32 v6, v7, v6
	v_div_scale_f32 v7, vcc, 1.0, v4, 1.0
	v_mul_f32_e32 v8, v7, v6
	v_fma_f32 v9, -v5, v8, v7
	v_fmac_f32_e32 v8, v9, v6
	v_fma_f32 v5, -v5, v8, v7
	v_div_fmas_f32 v5, v5, v6, v8
	v_div_fixup_f32 v4, v5, v4, 1.0
	ds_write_b32 v174, v4
.Lfill3_j1:
	s_or_b64 exec, exec, s[4:5]
	v_add_u32_e32 v174, 0x400, v174
	s_cmp_le_u32 s10, 2
	s_cbranch_scc1 .Lfill3_done
	v_mov_b32_e32 v4, v56
	v_mov_b32_e32 v5, v57
	v_mov_b32_e32 v6, v58
	v_mov_b32_e32 v7, v59
	v_mov_b32_e32 v8, v60
	v_mov_b32_e32 v9, v61
	v_mov_b32_e32 v10, v62
	v_mov_b32_e32 v11, v63
	v_mov_b32_e32 v12, v64
	v_mov_b32_e32 v13, v65
	v_mov_b32_e32 v14, v66
	v_mov_b32_e32 v15, v67
	v_mov_b32_e32 v16, v68
	v_mov_b32_e32 v17, v69
	v_mov_b32_e32 v18, v70
	v_mov_b32_e32 v19, v71
	v_add_f32_e32 v4, v4, v5
	v_add_f32_e32 v5, v6, v7
	v_add_f32_e32 v6, v8, v9
	v_add_f32_e32 v7, v10, v11
	v_add_f32_e32 v4, v4, v5
	v_add_f32_e32 v8, v12, v13
	v_add_f32_e32 v9, v14, v15
	v_add_f32_e32 v5, v6, v7
	v_add_f32_e32 v4, 0, v4
	v_add_f32_e32 v10, v16, v17
	v_add_f32_e32 v11, v18, v19
	v_add_f32_e32 v6, v8, v9
	v_add_f32_e32 v4, v4, v5
	v_add_f32_e32 v7, v10, v11
	v_add_f32_e32 v4, v4, v6
	v_add_f32_e32 v4, v4, v7
	v_lshlrev_b32_e32 v5, 2, v20
	ds_bpermute_b32 v5, v5, v4
	s_mov_b64 s[4:5], exec
	v_readlane_b32 s0, v237, 50
	v_readlane_b32 s1, v237, 51
	s_and_b64 s[0:1], s[4:5], s[0:1]
	s_mov_b64 exec, s[0:1]
	s_cbranch_execz .Lfill3_j2
	s_waitcnt lgkmcnt(0)
	v_add_f32_e32 v4, v4, v5
	v_fmamk_f32 v4, v4, 0x3a000000, v2
	v_mul_f32_e32 v5, 0x4f800000, v4
	v_cmp_gt_f32_e32 vcc, s7, v4
	s_nop 1
	v_cndmask_b32_e32 v4, v4, v5, vcc
	v_sqrt_f32_e32 v5, v4
	s_nop 0
	v_add_u32_e32 v6, -1, v5
	v_fma_f32 v8, -v6, v5, v4
	v_add_u32_e32 v7, 1, v5
	v_cmp_ge_f32_e64 s[0:1], 0, v8
	s_nop 1
	v_cndmask_b32_e64 v6, v5, v6, s[0:1]
	v_fma_f32 v5, -v7, v5, v4
	v_cmp_lt_f32_e64 s[0:1], 0, v5
	s_nop 1
	v_cndmask_b32_e64 v5, v6, v7, s[0:1]
	v_mul_f32_e32 v6, 0x37800000, v5
	v_cndmask_b32_e32 v5, v5, v6, vcc
	v_cmp_class_f32_e32 vcc, v4, v3
	s_nop 1
	v_cndmask_b32_e32 v4, v5, v4, vcc
	v_div_scale_f32 v5, s[0:1], v4, v4, 1.0
	v_rcp_f32_e32 v6, v5
	s_nop 0
	v_fma_f32 v7, -v5, v6, 1.0
	v_fmac_f32_e32 v6, v7, v6
	v_div_scale_f32 v7, vcc, 1.0, v4, 1.0
	v_mul_f32_e32 v8, v7, v6
	v_fma_f32 v9, -v5, v8, v7
	v_fmac_f32_e32 v8, v9, v6
	v_fma_f32 v5, -v5, v8, v7
	v_div_fmas_f32 v5, v5, v6, v8
	v_div_fixup_f32 v4, v5, v4, 1.0
	ds_write_b32 v174, v4
; template <class Sched> __device__ __forceinline__ void fill_rstd_table(PG8_LAS float* tab, const float* ssq, const Sched& S) {
;     ...
;     for (int i = 0; S.next(i, u); ++i) { const f32x4* p = (const f32x4*)(ssq + (size_t)(u.pm * BM + r) * 32 + hf * 16); float s = 0.f;
; #pragma unroll
;         for (int j = 0; j < 4; ++j) { const f32x4 a = p[j]; s += (a[0] + a[1]) + (a[2] + a[3]); }
;         s += __shfl_xor(s, 1);
;         if (hf == 0) tab[i * 256 + r] = 1.0f / sqrtf(s * (1.0f / 2048.0f) + RMS_EPS); }
.Lfill3_j2:
	s_or_b64 exec, exec, s[4:5]
	v_add_u32_e32 v174, 0x400, v174
	s_cmp_le_u32 s10, 3
	s_cbranch_scc1 .Lfill3_done
	v_mov_b32_e32 v4, v132
	v_mov_b32_e32 v5, v133
	v_mov_b32_e32 v6, v134
	v_mov_b32_e32 v7, v135
	v_mov_b32_e32 v8, v136
	v_mov_b32_e32 v9, v137
	v_mov_b32_e32 v10, v138
	v_mov_b32_e32 v11, v139
	v_mov_b32_e32 v12, v140
	v_mov_b32_e32 v13, v141
	v_mov_b32_e32 v14, v142
	v_mov_b32_e32 v15, v143
	v_mov_b32_e32 v16, v144
	v_mov_b32_e32 v17, v145
	v_mov_b32_e32 v18, v146
	v_mov_b32_e32 v19, v147
	v_add_f32_e32 v4, v4, v5
	v_add_f32_e32 v5, v6, v7
	v_add_f32_e32 v6, v8, v9
	v_add_f32_e32 v7, v10, v11
	v_add_f32_e32 v4, v4, v5
	v_add_f32_e32 v8, v12, v13
	v_add_f32_e32 v9, v14, v15
	v_add_f32_e32 v5, v6, v7
	v_add_f32_e32 v4, 0, v4
	v_add_f32_e32 v10, v16, v17
	v_add_f32_e32 v11, v18, v19
	v_add_f32_e32 v6, v8, v9
	v_add_f32_e32 v4, v4, v5
	v_add_f32_e32 v7, v10, v11
	v_add_f32_e32 v4, v4, v6
	v_add_f32_e32 v4, v4, v7
	v_lshlrev_b32_e32 v5, 2, v20
	ds_bpermute_b32 v5, v5, v4
	s_mov_b64 s[4:5], exec
	v_readlane_b32 s0, v237, 50
	v_readlane_b32 s1, v237, 51
	s_and_b64 s[0:1], s[4:5], s[0:1]
	s_mov_b64 exec, s[0:1]
	s_cbranch_execz .Lfill3_j3
	s_waitcnt lgkmcnt(0)
	v_add_f32_e32 v4, v4, v5
	v_fmamk_f32 v4, v4, 0x3a000000, v2
	v_mul_f32_e32 v5, 0x4f800000, v4
	v_cmp_gt_f32_e32 vcc, s7, v4
	s_nop 1
	v_cndmask_b32_e32 v4, v4, v5, vcc
	v_sqrt_f32_e32 v5, v4
	s_nop 0
	v_add_u32_e32 v6, -1, v5
	v_fma_f32 v8, -v6, v5, v4
	v_add_u32_e32 v7, 1, v5
	v_cmp_ge_f32_e64 s[0:1], 0, v8
	s_nop 1
	v_cndmask_b32_e64 v6, v5, v6, s[0:1]
	v_fma_f32 v5, -v7, v5, v4
	v_cmp_lt_f32_e64 s[0:1], 0, v5
	s_nop 1
	v_cndmask_b32_e64 v5, v6, v7, s[0:1]
	v_mul_f32_e32 v6, 0x37800000, v5
	v_cndmask_b32_e32 v5, v5, v6, vcc
	v_cmp_class_f32_e32 vcc, v4, v3
	s_nop 1
	v_cndmask_b32_e32 v4, v5, v4, vcc
	v_div_scale_f32 v5, s[0:1], v4, v4, 1.0
	v_rcp_f32_e32 v6, v5
	s_nop 0
	v_fma_f32 v7, -v5, v6, 1.0
	v_fmac_f32_e32 v6, v7, v6
	v_div_scale_f32 v7, vcc, 1.0, v4, 1.0
	v_mul_f32_e32 v8, v7, v6
	v_fma_f32 v9, -v5, v8, v7
	v_fmac_f32_e32 v8, v9, v6
	v_fma_f32 v5, -v5, v8, v7
	v_div_fmas_f32 v5, v5, v6, v8
	v_div_fixup_f32 v4, v5, v4, 1.0
	ds_write_b32 v174, v4
.Lfill3_j3:
	s_or_b64 exec, exec, s[4:5]
	v_add_u32_e32 v174, 0x400, v174
	s_cmp_le_u32 s10, 4
	s_cbranch_scc1 .Lfill3_done
	v_mov_b32_e32 v4, v148
	v_mov_b32_e32 v5, v149
	v_mov_b32_e32 v6, v150
	v_mov_b32_e32 v7, v151
	v_mov_b32_e32 v8, v152
	v_mov_b32_e32 v9, v153
	v_mov_b32_e32 v10, v154
	v_mov_b32_e32 v11, v155
	v_mov_b32_e32 v12, v156
	v_mov_b32_e32 v13, v157
	v_mov_b32_e32 v14, v158
	v_mov_b32_e32 v15, v159
	v_mov_b32_e32 v16, v160
	v_mov_b32_e32 v17, v161
	v_mov_b32_e32 v18, v162
	v_mov_b32_e32 v19, v163
	v_add_f32_e32 v4, v4, v5
	v_add_f32_e32 v5, v6, v7
	v_add_f32_e32 v6, v8, v9
	v_add_f32_e32 v7, v10, v11
	v_add_f32_e32 v4, v4, v5
	v_add_f32_e32 v8, v12, v13
	v_add_f32_e32 v9, v14, v15
	v_add_f32_e32 v5, v6, v7
	v_add_f32_e32 v4, 0, v4
	v_add_f32_e32 v10, v16, v17
	v_add_f32_e32 v11, v18, v19
	v_add_f32_e32 v6, v8, v9
	v_add_f32_e32 v4, v4, v5
	v_add_f32_e32 v7, v10, v11
	v_add_f32_e32 v4, v4, v6
	v_add_f32_e32 v4, v4, v7
	v_lshlrev_b32_e32 v5, 2, v20
	ds_bpermute_b32 v5, v5, v4
	s_mov_b64 s[4:5], exec
	v_readlane_b32 s0, v237, 50
	v_readlane_b32 s1, v237, 51
	s_and_b64 s[0:1], s[4:5], s[0:1]
	s_mov_b64 exec, s[0:1]
	s_cbranch_execz .Lfill3_j4
	s_waitcnt lgkmcnt(0)
	v_add_f32_e32 v4, v4, v5
	v_fmamk_f32 v4, v4, 0x3a000000, v2
	v_mul_f32_e32 v5, 0x4f800000, v4
	v_cmp_gt_f32_e32 vcc, s7, v4
	s_nop 1
	v_cndmask_b32_e32 v4, v4, v5, vcc
	v_sqrt_f32_e32 v5, v4
	s_nop 0
	v_add_u32_e32 v6, -1, v5
	v_fma_f32 v8, -v6, v5, v4
	v_add_u32_e32 v7, 1, v5
	v_cmp_ge_f32_e64 s[0:1], 0, v8
	s_nop 1
	v_cndmask_b32_e64 v6, v5, v6, s[0:1]
	v_fma_f32 v5, -v7, v5, v4
	v_cmp_lt_f32_e64 s[0:1], 0, v5
	s_nop 1
	v_cndmask_b32_e64 v5, v6, v7, s[0:1]
	v_mul_f32_e32 v6, 0x37800000, v5
	v_cndmask_b32_e32 v5, v5, v6, vcc
	v_cmp_class_f32_e32 vcc, v4, v3
	s_nop 1
	v_cndmask_b32_e32 v4, v5, v4, vcc
	v_div_scale_f32 v5, s[0:1], v4, v4, 1.0
	v_rcp_f32_e32 v6, v5
	s_nop 0
	v_fma_f32 v7, -v5, v6, 1.0
	v_fmac_f32_e32 v6, v7, v6
	v_div_scale_f32 v7, vcc, 1.0, v4, 1.0
	v_mul_f32_e32 v8, v7, v6
	v_fma_f32 v9, -v5, v8, v7
	v_fmac_f32_e32 v8, v9, v6
	v_fma_f32 v5, -v5, v8, v7
	v_div_fmas_f32 v5, v5, v6, v8
	v_div_fixup_f32 v4, v5, v4, 1.0
	ds_write_b32 v174, v4
.Lfill3_j4:
	s_or_b64 exec, exec, s[4:5]
	v_add_u32_e32 v174, 0x400, v174
	s_cmp_le_u32 s10, 5
	s_cbranch_scc1 .Lfill3_done
	v_mov_b32_e32 v4, v180
	v_mov_b32_e32 v5, v181
	v_mov_b32_e32 v6, v182
	v_mov_b32_e32 v7, v183
	v_mov_b32_e32 v8, v184
	v_mov_b32_e32 v9, v185
	v_mov_b32_e32 v10, v186
	v_mov_b32_e32 v11, v187
	v_mov_b32_e32 v12, v188
	v_mov_b32_e32 v13, v189
	v_mov_b32_e32 v14, v190
	v_mov_b32_e32 v15, v191
	v_mov_b32_e32 v16, v192
	v_mov_b32_e32 v17, v193
	v_mov_b32_e32 v18, v194
	v_mov_b32_e32 v19, v195
	v_add_f32_e32 v4, v4, v5
	v_add_f32_e32 v5, v6, v7
	v_add_f32_e32 v6, v8, v9
	v_add_f32_e32 v7, v10, v11
	v_add_f32_e32 v4, v4, v5
	v_add_f32_e32 v8, v12, v13
	v_add_f32_e32 v9, v14, v15
	v_add_f32_e32 v5, v6, v7
	v_add_f32_e32 v4, 0, v4
	v_add_f32_e32 v10, v16, v17
	v_add_f32_e32 v11, v18, v19
	v_add_f32_e32 v6, v8, v9
	v_add_f32_e32 v4, v4, v5
	v_add_f32_e32 v7, v10, v11
	v_add_f32_e32 v4, v4, v6
	v_add_f32_e32 v4, v4, v7
	v_lshlrev_b32_e32 v5, 2, v20
	ds_bpermute_b32 v5, v5, v4
	s_mov_b64 s[4:5], exec
	v_readlane_b32 s0, v237, 50
	v_readlane_b32 s1, v237, 51
	s_and_b64 s[0:1], s[4:5], s[0:1]
	s_mov_b64 exec, s[0:1]
	s_cbranch_execz .Lfill3_j5
	s_waitcnt lgkmcnt(0)
	v_add_f32_e32 v4, v4, v5
	v_fmamk_f32 v4, v4, 0x3a000000, v2
	v_mul_f32_e32 v5, 0x4f800000, v4
	v_cmp_gt_f32_e32 vcc, s7, v4
	s_nop 1
	v_cndmask_b32_e32 v4, v4, v5, vcc
	v_sqrt_f32_e32 v5, v4
	s_nop 0
	v_add_u32_e32 v6, -1, v5
	v_fma_f32 v8, -v6, v5, v4
	v_add_u32_e32 v7, 1, v5
	v_cmp_ge_f32_e64 s[0:1], 0, v8
	s_nop 1
	v_cndmask_b32_e64 v6, v5, v6, s[0:1]
	v_fma_f32 v5, -v7, v5, v4
	v_cmp_lt_f32_e64 s[0:1], 0, v5
	s_nop 1
	v_cndmask_b32_e64 v5, v6, v7, s[0:1]
	v_mul_f32_e32 v6, 0x37800000, v5
	v_cndmask_b32_e32 v5, v5, v6, vcc
	v_cmp_class_f32_e32 vcc, v4, v3
	s_nop 1
	v_cndmask_b32_e32 v4, v5, v4, vcc
	v_div_scale_f32 v5, s[0:1], v4, v4, 1.0
	v_rcp_f32_e32 v6, v5
	s_nop 0
	v_fma_f32 v7, -v5, v6, 1.0
	v_fmac_f32_e32 v6, v7, v6
	v_div_scale_f32 v7, vcc, 1.0, v4, 1.0
	v_mul_f32_e32 v8, v7, v6
	v_fma_f32 v9, -v5, v8, v7
	v_fmac_f32_e32 v8, v9, v6
	v_fma_f32 v5, -v5, v8, v7
	v_div_fmas_f32 v5, v5, v6, v8
	v_div_fixup_f32 v4, v5, v4, 1.0
	ds_write_b32 v174, v4
.Lfill3_j5:
	s_or_b64 exec, exec, s[4:5]
	v_add_u32_e32 v174, 0x400, v174
